# C item LayerNorm: (f-mu)*rstd as one fma, bf16 rounding by v_cvt_pk_bf16_f32 instead of the bfe/add3 sequence (2 VALU fewer per element)
# baseline (speedup 1.0000x reference)
.LBB0_779:
	v_mov_b32_e32 v43, v0
	s_ashr_i32 s5, s3, 31
	v_ashrrev_i32_e32 v44, 7, v43
	s_waitcnt vmcnt(2)
	v_add_u32_e32 v164, s2, v44
	v_ashrrev_i32_e32 v165, 31, v164
	v_and_b32_e32 v168, 31, v43
	s_waitcnt vmcnt(0)
	v_lshlrev_b64 v[2:3], 15, v[164:165]
	v_bfe_u32 v169, v43, 5, 1
	v_lshl_add_u64 v[2:3], s[56:57], 0, v[2:3]
	v_lshlrev_b32_e32 v154, 8, v168
	v_lshl_add_u64 v[2:3], v[2:3], 0, v[154:155]
	v_lshlrev_b32_e32 v154, 4, v169
	v_lshl_add_u64 v[18:19], v[2:3], 0, v[154:155]
	v_add_co_u32_e32 v20, vcc, s14, v18
	v_ashrrev_i32_e32 v45, 2, v43
	s_nop 0
	v_addc_co_u32_e32 v21, vcc, 0, v19, vcc
	v_add_co_u32_e32 v22, vcc, s17, v18
	global_load_dwordx4 v[2:5], v[18:19], off
	global_load_dwordx4 v[6:9], v[20:21], off
	v_addc_co_u32_e32 v23, vcc, 0, v19, vcc
	v_add_co_u32_e32 v24, vcc, s30, v18
	global_load_dwordx4 v[10:13], v[22:23], off
	s_nop 0
	v_addc_co_u32_e32 v25, vcc, 0, v19, vcc
	global_load_dwordx4 v[14:17], v[24:25], off
	global_load_dwordx4 v[138:141], v[18:19], off offset:32
	global_load_dwordx4 v[142:145], v[20:21], off offset:32
	global_load_dwordx4 v[146:149], v[22:23], off offset:32
	global_load_dwordx4 v[150:153], v[24:25], off offset:32
	global_load_dwordx4 v[126:129], v[20:21], off offset:64
	global_load_dwordx4 v[130:133], v[22:23], off offset:64
	global_load_dwordx4 v[134:137], v[24:25], off offset:64
	global_load_dwordx4 v[114:117], v[20:21], off offset:96
	global_load_dwordx4 v[118:121], v[22:23], off offset:96
	global_load_dwordx4 v[122:125], v[24:25], off offset:96
	global_load_dwordx4 v[106:109], v[22:23], off offset:128
	global_load_dwordx4 v[110:113], v[24:25], off offset:128
	global_load_dwordx4 v[98:101], v[22:23], off offset:160
	global_load_dwordx4 v[102:105], v[24:25], off offset:160
	global_load_dwordx4 v[94:97], v[24:25], off offset:192
	global_load_dwordx4 v[90:93], v[24:25], off offset:224
	v_add_u32_e32 v18, s3, v45
	v_ashrrev_i32_e32 v19, 31, v18
	v_lshlrev_b32_e32 v20, 6, v43
	v_lshlrev_b64 v[18:19], 12, v[18:19]
	v_and_b32_e32 v46, 0xc0, v20
	v_lshl_add_u64 v[18:19], s[60:61], 0, v[18:19]
	v_lshlrev_b32_e32 v20, 1, v46
	v_mov_b32_e32 v21, v155
	v_lshl_add_u64 v[34:35], v[18:19], 0, v[20:21]
	global_load_dwordx4 v[18:21], v[34:35], off offset:3632
	global_load_dwordx4 v[22:25], v[34:35], off offset:3616
	global_load_dwordx4 v[26:29], v[34:35], off offset:3600
	global_load_dwordx4 v[30:33], v[34:35], off offset:3584
	global_load_dwordx4 v[36:39], v[34:35], off offset:3680
	global_load_dwordx4 v[202:205], v[34:35], off offset:3664
	global_load_dwordx4 v[48:51], v[34:35], off offset:3648
	global_load_dwordx4 v[206:209], v[34:35], off offset:3696
	v_and_b32_e32 v215, 31, v0
	v_add_u32_e32 v215, s3, v215
	v_lshlrev_b32_e32 v215, 12, v215
	v_and_b32_e32 v245, 0x1c0, v0
	v_add_u32_e32 v215, v215, v245
	v_bfe_u32 v245, v0, 5, 1
	v_lshl_add_u32 v215, v245, 3, v215
	global_load_dwordx2 v[216:217], v215, s[60:61] offset:3072
	global_load_dwordx2 v[218:219], v215, s[60:61] offset:3088
	global_load_dwordx2 v[220:221], v215, s[60:61] offset:3104
	global_load_dwordx2 v[222:223], v215, s[60:61] offset:3120
	s_add_u32 s98, s60, 0x20000
	s_addc_u32 s99, s61, 0
	global_load_dwordx2 v[224:225], v215, s[98:99] offset:3072
	global_load_dwordx2 v[226:227], v215, s[98:99] offset:3088
	global_load_dwordx2 v[228:229], v215, s[98:99] offset:3104
	global_load_dwordx2 v[230:231], v215, s[98:99] offset:3120
	s_add_u32 s100, s60, 0x40000
	s_addc_u32 s101, s61, 0
	global_load_dwordx2 v[232:233], v215, s[100:101] offset:3072
	global_load_dwordx2 v[234:235], v215, s[100:101] offset:3088
	global_load_dwordx2 v[236:237], v215, s[100:101] offset:3104
	global_load_dwordx2 v[238:239], v215, s[100:101] offset:3120
	s_add_u32 s98, s60, 0x60000
	s_addc_u32 s99, s61, 0
	global_load_dwordx2 v[240:241], v215, s[98:99] offset:3072
	global_load_dwordx2 v[246:247], v215, s[98:99] offset:3088
	global_load_dwordx2 v[252:253], v215, s[98:99] offset:3104
	global_load_dwordx2 v[254:255], v215, s[98:99] offset:3120
	v_lshrrev_b32_e32 v42, 5, v43
	s_add_i32 s4, s4, s46
	s_waitcnt vmcnt(23)
	v_lshlrev_b32_e32 v178, 16, v18
	s_waitcnt vmcnt(22)
	v_lshlrev_b32_e32 v186, 16, v22
	s_waitcnt vmcnt(21)
	v_lshlrev_b32_e32 v194, 16, v26
	s_waitcnt vmcnt(20)
	v_lshlrev_b32_e32 v200, 16, v30
	v_and_b32_e32 v199, 0xffff0000, v30
	v_add_f32_e32 v30, 0, v200
	v_lshlrev_b32_e32 v198, 16, v31
	v_add_f32_e32 v30, v30, v199
	v_and_b32_e32 v197, 0xffff0000, v31
	v_mul_f32_e32 v31, v199, v199
	v_add_f32_e32 v30, v30, v198
	v_lshlrev_b32_e32 v196, 16, v32
	v_fmac_f32_e32 v31, v200, v200
	v_add_f32_e32 v30, v30, v197
	v_and_b32_e32 v195, 0xffff0000, v32
	v_fmac_f32_e32 v31, v198, v198
	v_add_f32_e32 v30, v30, v196
	v_lshlrev_b32_e32 v193, 16, v33
	v_fmac_f32_e32 v31, v197, v197
	v_add_f32_e32 v30, v30, v195
	v_and_b32_e32 v191, 0xffff0000, v33
	v_fmac_f32_e32 v31, v196, v196
	v_add_f32_e32 v30, v30, v193
	v_fmac_f32_e32 v31, v195, v195
	v_add_f32_e32 v30, v30, v191
	v_fmac_f32_e32 v31, v193, v193
	v_and_b32_e32 v192, 0xffff0000, v26
	v_add_f32_e32 v26, v30, v194
	v_fmac_f32_e32 v31, v191, v191
	v_lshlrev_b32_e32 v190, 16, v27
	v_add_f32_e32 v26, v26, v192
	v_and_b32_e32 v189, 0xffff0000, v27
	v_fmac_f32_e32 v31, v194, v194
	v_add_f32_e32 v26, v26, v190
	v_lshlrev_b32_e32 v188, 16, v28
	v_fmac_f32_e32 v31, v192, v192
	v_add_f32_e32 v26, v26, v189
	v_and_b32_e32 v187, 0xffff0000, v28
	v_fmac_f32_e32 v31, v190, v190
	v_add_f32_e32 v26, v26, v188
	v_lshlrev_b32_e32 v184, 16, v29
	v_fmac_f32_e32 v31, v189, v189
	v_add_f32_e32 v26, v26, v187
	v_and_b32_e32 v182, 0xffff0000, v29
	v_fmac_f32_e32 v31, v188, v188
	v_add_f32_e32 v26, v26, v184
	v_fmac_f32_e32 v31, v187, v187
	v_add_f32_e32 v26, v26, v182
	v_fmac_f32_e32 v31, v184, v184
	v_and_b32_e32 v185, 0xffff0000, v22
	v_add_f32_e32 v22, v26, v186
	v_fmac_f32_e32 v31, v182, v182
	v_lshlrev_b32_e32 v183, 16, v23
	v_add_f32_e32 v22, v22, v185
	v_and_b32_e32 v179, 0xffff0000, v23
	v_fmac_f32_e32 v31, v186, v186
	v_add_f32_e32 v22, v22, v183
	v_lshlrev_b32_e32 v177, 16, v24
	v_fmac_f32_e32 v31, v185, v185
	v_add_f32_e32 v22, v22, v179
	v_and_b32_e32 v175, 0xffff0000, v24
	v_fmac_f32_e32 v31, v183, v183
	v_add_f32_e32 v22, v22, v177
	v_lshlrev_b32_e32 v173, 16, v25
	v_fmac_f32_e32 v31, v179, v179
	v_add_f32_e32 v22, v22, v175
	v_and_b32_e32 v171, 0xffff0000, v25
	v_fmac_f32_e32 v31, v177, v177
	v_add_f32_e32 v22, v22, v173
	v_fmac_f32_e32 v31, v175, v175
	v_add_f32_e32 v22, v22, v171
	v_fmac_f32_e32 v31, v173, v173
	v_and_b32_e32 v176, 0xffff0000, v18
	v_add_f32_e32 v18, v22, v178
	v_fmac_f32_e32 v31, v171, v171
	v_lshlrev_b32_e32 v174, 16, v19
	v_add_f32_e32 v18, v18, v176
	v_and_b32_e32 v172, 0xffff0000, v19
	v_fmac_f32_e32 v31, v178, v178
	v_add_f32_e32 v18, v18, v174
	v_lshlrev_b32_e32 v167, 16, v20
	v_fmac_f32_e32 v31, v176, v176
	v_add_f32_e32 v18, v18, v172
	v_and_b32_e32 v165, 0xffff0000, v20
	v_fmac_f32_e32 v31, v174, v174
	v_add_f32_e32 v18, v18, v167
	v_lshlrev_b32_e32 v64, 16, v21
	v_fmac_f32_e32 v31, v172, v172
	v_add_f32_e32 v18, v18, v165
	v_and_b32_e32 v62, 0xffff0000, v21
	v_fmac_f32_e32 v31, v167, v167
	v_add_f32_e32 v18, v18, v64
	v_fmac_f32_e32 v31, v165, v165
	v_add_f32_e32 v18, v18, v62
	s_waitcnt vmcnt(17)
	v_lshlrev_b32_e32 v170, 16, v48
	v_fmac_f32_e32 v31, v64, v64
	v_and_b32_e32 v166, 0xffff0000, v48
	v_add_f32_e32 v18, v18, v170
	v_fmac_f32_e32 v31, v62, v62
	v_lshlrev_b32_e32 v65, 16, v49
	v_add_f32_e32 v18, v18, v166
	v_and_b32_e32 v63, 0xffff0000, v49
	v_fmac_f32_e32 v31, v170, v170
	v_add_f32_e32 v18, v18, v65
	v_lshlrev_b32_e32 v60, 16, v50
	v_fmac_f32_e32 v31, v166, v166
	v_add_f32_e32 v18, v18, v63
	v_and_b32_e32 v59, 0xffff0000, v50
	v_fmac_f32_e32 v31, v65, v65
	v_add_f32_e32 v18, v18, v60
	v_lshlrev_b32_e32 v57, 16, v51
	v_fmac_f32_e32 v31, v63, v63
	v_add_f32_e32 v18, v18, v59
	v_and_b32_e32 v55, 0xffff0000, v51
	v_fmac_f32_e32 v31, v60, v60
	v_add_f32_e32 v18, v18, v57
	v_fmac_f32_e32 v31, v59, v59
	v_add_f32_e32 v18, v18, v55
	v_lshlrev_b32_e32 v61, 16, v202
	v_fmac_f32_e32 v31, v57, v57
	v_and_b32_e32 v58, 0xffff0000, v202
	v_add_f32_e32 v18, v18, v61
	v_fmac_f32_e32 v31, v55, v55
	v_lshlrev_b32_e32 v56, 16, v203
	v_add_f32_e32 v18, v18, v58
	v_and_b32_e32 v54, 0xffff0000, v203
	v_fmac_f32_e32 v31, v61, v61
	v_add_f32_e32 v18, v18, v56
	v_lshlrev_b32_e32 v53, 16, v204
	v_fmac_f32_e32 v31, v58, v58
	v_add_f32_e32 v18, v18, v54
	v_and_b32_e32 v51, 0xffff0000, v204
	v_fmac_f32_e32 v31, v56, v56
	v_add_f32_e32 v18, v18, v53
	v_lshlrev_b32_e32 v49, 16, v205
	v_fmac_f32_e32 v31, v54, v54
	v_add_f32_e32 v18, v18, v51
	v_and_b32_e32 v47, 0xffff0000, v205
	v_fmac_f32_e32 v31, v53, v53
	v_add_f32_e32 v18, v18, v49
	v_fmac_f32_e32 v31, v51, v51
	v_add_f32_e32 v18, v18, v47
	v_lshlrev_b32_e32 v52, 16, v36
	v_fmac_f32_e32 v31, v49, v49
	v_and_b32_e32 v50, 0xffff0000, v36
	v_add_f32_e32 v18, v18, v52
	v_fmac_f32_e32 v31, v47, v47
	v_lshlrev_b32_e32 v48, 16, v37
	v_add_f32_e32 v18, v18, v50
	v_fmac_f32_e32 v31, v52, v52
	v_add_f32_e32 v18, v18, v48
	v_and_b32_e32 v37, 0xffff0000, v37
	v_fmac_f32_e32 v31, v50, v50
	v_lshlrev_b32_e32 v34, 16, v38
	v_mov_b32_e32 v35, v37
	v_add_f32_e32 v20, v18, v37
	v_fmac_f32_e32 v31, v48, v48
	v_and_b32_e32 v24, 0xffff0000, v38
	v_pk_mul_f32 v[18:19], v[34:35], v[34:35]
	v_add_f32_e32 v20, v20, v34
	v_lshlrev_b32_e32 v25, 16, v39
	v_add_f32_e32 v19, v19, v31
	v_add_f32_e32 v20, v20, v24
	v_add_f32_e32 v21, v18, v19
	v_pk_mul_f32 v[18:19], v[24:25], v[24:25]
	v_add_f32_e32 v20, v20, v25
	v_and_b32_e32 v33, 0xffff0000, v39
	v_add_f32_e32 v18, v18, v21
	s_waitcnt vmcnt(16)
	v_lshlrev_b32_e32 v28, 16, v206
	v_mov_b32_e32 v29, v33
	v_add_f32_e32 v20, v20, v33
	v_add_f32_e32 v21, v19, v18
	v_and_b32_e32 v22, 0xffff0000, v206
	v_pk_mul_f32 v[18:19], v[28:29], v[28:29]
	v_add_f32_e32 v20, v20, v28
	v_lshlrev_b32_e32 v23, 16, v207
	v_add_f32_e32 v19, v19, v21
	v_add_f32_e32 v20, v20, v22
	v_add_f32_e32 v21, v18, v19
	v_pk_mul_f32 v[18:19], v[22:23], v[22:23]
	v_add_f32_e32 v29, v20, v23
	v_and_b32_e32 v31, 0xffff0000, v207
	v_add_f32_e32 v18, v18, v21
	v_lshlrev_b32_e32 v26, 16, v208
	v_mov_b32_e32 v27, v31
	v_add_f32_e32 v29, v29, v31
	v_and_b32_e32 v36, s0, v38
	v_add_f32_e32 v18, v19, v18
	v_and_b32_e32 v20, 0xffff0000, v208
	v_pk_mul_f32 v[38:39], v[26:27], v[26:27]
	v_add_f32_e32 v27, v29, v26
	v_lshlrev_b32_e32 v21, 16, v209
	v_add_f32_e32 v18, v39, v18
	v_add_f32_e32 v27, v27, v20
	v_and_b32_e32 v29, 64, v181
	v_add_f32_e32 v18, v38, v18
	v_pk_mul_f32 v[40:41], v[20:21], v[20:21]
	v_add_f32_e32 v39, v27, v21
	v_xor_b32_e32 v27, 1, v181
	v_add_u32_e32 v29, 64, v29
	v_and_b32_e32 v19, 0xffff0000, v209
	v_add_f32_e32 v18, v40, v18
	v_cmp_lt_i32_e32 vcc, v27, v29
	v_add_f32_e32 v18, v41, v18
	v_mul_f32_e32 v38, v19, v19
	v_cndmask_b32_e32 v27, v181, v27, vcc
	v_lshlrev_b32_e32 v27, 2, v27
	v_pk_add_f32 v[38:39], v[38:39], v[18:19]
	ds_bpermute_b32 v41, v27, v39
	ds_bpermute_b32 v40, v27, v38
	v_xor_b32_e32 v35, 2, v181
	v_cmp_lt_i32_e32 vcc, v35, v29
	v_and_b32_e32 v30, s0, v206
	v_mov_b32_e32 v32, v36
	v_cndmask_b32_e32 v29, v181, v35, vcc
	v_lshlrev_b32_e32 v29, 2, v29
	s_waitcnt lgkmcnt(0)
	v_pk_add_f32 v[38:39], v[38:39], v[40:41]
	ds_bpermute_b32 v41, v29, v39
	ds_bpermute_b32 v40, v29, v38
	s_waitcnt lgkmcnt(0)
	v_pk_add_f32 v[40:41], v[38:39], v[40:41]
	s_nop 0
	v_pk_mul_f32 v[38:39], v[40:41], s[22:23] op_sel_hi:[1,0]
	v_pk_fma_f32 v[36:37], v[40:41], s[22:23], v[36:37] op_sel_hi:[1,0,1] neg_lo:[1,0,0] neg_hi:[1,0,0]
	v_fma_f32 v18, -v39, v39, v38
	v_max_f32_e32 v18, 0, v18
	v_add_f32_e32 v18, 0x358637bd, v18
	v_cmp_gt_f32_e32 vcc, s33, v18
	v_mul_f32_e32 v27, 0x4b800000, v18
	v_sub_f32_e32 v29, v200, v39
	v_cndmask_b32_e32 v18, v18, v27, vcc
	v_rsq_f32_e32 v18, v18
	v_sub_f32_e32 v19, v19, v39
	v_mul_f32_e32 v27, 0x45800000, v18
	v_cndmask_b32_e32 v18, v18, v27, vcc
	v_mul_f32_e32 v29, v29, v18
	v_lshlrev_b32_e32 v27, 1, v45
	v_bfe_u32 v35, v29, 16, 1
	v_ashrrev_i32_e32 v45, 1, v43
	v_and_b32_e32 v27, 14, v27
	v_add3_u32 v29, v29, v35, s15
	v_lshl_add_u32 v35, v46, 8, 32
	v_and_b32_e32 v46, -16, v45
	v_add3_u32 v200, v35, v46, v27
	ds_write_b16_d16_hi v200, v29 offset:55296
	v_mul_f32_e64 v215, -v39, v18
	v_fma_f32 v29, v199, v18, v215
	v_cvt_pk_bf16_f32 v29, v29, v29
	v_bitop3_b32 v199, v45, 16, -16 bitop3:0x6c
	v_add3_u32 v201, v35, v199, v27
	ds_write_b16 v201, v29 offset:55552
	v_fma_f32 v29, v198, v18, v215
	v_cvt_pk_bf16_f32 v29, v29, v29
	v_bitop3_b32 v198, v45, 32, -16 bitop3:0x6c
	v_add3_u32 v202, v35, v198, v27
	ds_write_b16 v202, v29 offset:55808
	v_fma_f32 v29, v197, v18, v215
	v_cvt_pk_bf16_f32 v29, v29, v29
	v_bitop3_b32 v197, v45, 48, -16 bitop3:0x6c
	v_add3_u32 v203, v35, v197, v27
	ds_write_b16 v203, v29 offset:56064
	v_fma_f32 v29, v196, v18, v215
	v_cvt_pk_bf16_f32 v29, v29, v29
	v_bitop3_b32 v196, v45, 64, -16 bitop3:0x6c
	v_add3_u32 v204, v35, v196, v27
	ds_write_b16 v204, v29 offset:56320
	v_fma_f32 v29, v195, v18, v215
	v_cvt_pk_bf16_f32 v29, v29, v29
	v_bitop3_b32 v195, v45, s34, -16 bitop3:0x6c
	v_add3_u32 v205, v35, v195, v27
	ds_write_b16 v205, v29 offset:56576
	v_fma_f32 v29, v193, v18, v215
	v_cvt_pk_bf16_f32 v29, v29, v29
	v_bitop3_b32 v193, v45, s31, -16 bitop3:0x6c
	v_add3_u32 v206, v35, v193, v27
	ds_write_b16 v206, v29 offset:56832
	v_fma_f32 v29, v191, v18, v215
	v_cvt_pk_bf16_f32 v29, v29, v29
	v_bitop3_b32 v191, v45, s13, -16 bitop3:0x6c
	v_add3_u32 v207, v35, v191, v27
	ds_write_b16 v207, v29 offset:57088
	v_fma_f32 v29, v194, v18, v215
	v_cvt_pk_bf16_f32 v29, v29, v29
	v_bitop3_b32 v194, v45, s12, -16 bitop3:0x6c
	v_add3_u32 v208, v35, v194, v27
	ds_write_b16 v208, v29 offset:57344
	v_fma_f32 v29, v192, v18, v215
	v_cvt_pk_bf16_f32 v29, v29, v29
	v_bitop3_b32 v192, v45, s35, -16 bitop3:0x6c
	v_add3_u32 v209, v35, v192, v27
	ds_write_b16 v209, v29 offset:57600
	v_fma_f32 v29, v190, v18, v215
	v_cvt_pk_bf16_f32 v29, v29, v29
	v_bitop3_b32 v190, v45, s36, -16 bitop3:0x6c
	v_add3_u32 v210, v35, v190, v27
	ds_write_b16 v210, v29 offset:57856
	v_fma_f32 v29, v189, v18, v215
	v_cvt_pk_bf16_f32 v29, v29, v29
	v_bitop3_b32 v189, v45, s37, -16 bitop3:0x6c
	v_add3_u32 v211, v35, v189, v27
	ds_write_b16 v211, v29 offset:58112
	v_fma_f32 v29, v188, v18, v215
	v_cvt_pk_bf16_f32 v29, v29, v29
	v_bitop3_b32 v188, v45, s16, -16 bitop3:0x6c
	v_add3_u32 v212, v35, v188, v27
	ds_write_b16 v212, v29 offset:58368
	v_fma_f32 v29, v187, v18, v215
	v_cvt_pk_bf16_f32 v29, v29, v29
	v_bitop3_b32 v187, v45, s42, -16 bitop3:0x6c
	v_add3_u32 v213, v35, v187, v27
	ds_write_b16 v213, v29 offset:58624
	v_fma_f32 v29, v184, v18, v215
	v_cvt_pk_bf16_f32 v29, v29, v29
	v_bitop3_b32 v184, v45, s43, -16 bitop3:0x6c
	v_add3_u32 v214, v35, v184, v27
	ds_write_b16 v214, v29 offset:58880
	v_sub_f32_e32 v29, v182, v39
	v_mul_f32_e32 v29, v29, v18
	v_bfe_u32 v182, v29, 16, 1
	v_bitop3_b32 v45, v45, s94, -16 bitop3:0x6c
	v_add_u32_e32 v38, 0xd800, v35
	v_add3_u32 v29, v29, v182, s15
	v_add3_u32 v35, v35, v45, v27
	ds_write_b16_d16_hi v35, v29 offset:59136
	v_fma_f32 v29, v186, v18, v215
	v_cvt_pk_bf16_f32 v29, v29, v29
	ds_write_b16 v200, v29 offset:59392
	v_fma_f32 v29, v185, v18, v215
	v_cvt_pk_bf16_f32 v29, v29, v29
	ds_write_b16 v201, v29 offset:59648
	v_fma_f32 v29, v183, v18, v215
	v_cvt_pk_bf16_f32 v29, v29, v29
	ds_write_b16 v202, v29 offset:59904
	v_fma_f32 v29, v179, v18, v215
	v_cvt_pk_bf16_f32 v29, v29, v29
	ds_write_b16 v203, v29 offset:60160
	v_fma_f32 v29, v177, v18, v215
	v_cvt_pk_bf16_f32 v29, v29, v29
	ds_write_b16 v204, v29 offset:60416
	v_fma_f32 v29, v175, v18, v215
	v_cvt_pk_bf16_f32 v29, v29, v29
	ds_write_b16 v205, v29 offset:60672
	v_fma_f32 v29, v173, v18, v215
	v_cvt_pk_bf16_f32 v29, v29, v29
	ds_write_b16 v206, v29 offset:60928
	v_fma_f32 v29, v171, v18, v215
	v_cvt_pk_bf16_f32 v29, v29, v29
	ds_write_b16 v207, v29 offset:61184
	v_fma_f32 v29, v178, v18, v215
	v_cvt_pk_bf16_f32 v29, v29, v29
	ds_write_b16 v208, v29 offset:61440
	v_fma_f32 v29, v176, v18, v215
	v_cvt_pk_bf16_f32 v29, v29, v29
	ds_write_b16 v209, v29 offset:61696
	v_fma_f32 v29, v174, v18, v215
	v_cvt_pk_bf16_f32 v29, v29, v29
	ds_write_b16 v210, v29 offset:61952
	v_fma_f32 v29, v172, v18, v215
	v_cvt_pk_bf16_f32 v29, v29, v29
	ds_write_b16 v211, v29 offset:62208
	v_fma_f32 v29, v167, v18, v215
	v_cvt_pk_bf16_f32 v29, v29, v29
	ds_write_b16 v212, v29 offset:62464
	v_fma_f32 v29, v165, v18, v215
	v_cvt_pk_bf16_f32 v29, v29, v29
	ds_write_b16 v213, v29 offset:62720
	v_fma_f32 v29, v64, v18, v215
	v_cvt_pk_bf16_f32 v29, v29, v29
	ds_write_b16 v214, v29 offset:62976
	v_fma_f32 v29, v62, v18, v215
	v_cvt_pk_bf16_f32 v29, v29, v29
	ds_write_b16 v35, v29 offset:63232
	v_fma_f32 v29, v170, v18, v215
	v_cvt_pk_bf16_f32 v29, v29, v29
	ds_write_b16 v200, v29 offset:63488
	v_fma_f32 v29, v166, v18, v215
	v_cvt_pk_bf16_f32 v29, v29, v29
	ds_write_b16 v201, v29 offset:63744
	v_fma_f32 v29, v65, v18, v215
	v_cvt_pk_bf16_f32 v29, v29, v29
	ds_write_b16 v202, v29 offset:64000
	v_fma_f32 v29, v63, v18, v215
	v_cvt_pk_bf16_f32 v29, v29, v29
	ds_write_b16 v203, v29 offset:64256
	v_fma_f32 v29, v60, v18, v215
	v_cvt_pk_bf16_f32 v29, v29, v29
	ds_write_b16 v204, v29 offset:64512
	v_fma_f32 v29, v59, v18, v215
	v_cvt_pk_bf16_f32 v29, v29, v29
	ds_write_b16 v205, v29 offset:64768
	v_fma_f32 v29, v57, v18, v215
	v_cvt_pk_bf16_f32 v29, v29, v29
	ds_write_b16 v206, v29 offset:65024
	v_fma_f32 v29, v55, v18, v215
	v_cvt_pk_bf16_f32 v29, v29, v29
	ds_write_b16 v207, v29 offset:65280
	v_fma_f32 v29, v61, v18, v215
	v_cvt_pk_bf16_f32 v29, v29, v29
	v_add3_u32 v35, v38, v194, v27
	ds_write_b16 v35, v29 offset:10240
	v_fma_f32 v29, v58, v18, v215
	v_cvt_pk_bf16_f32 v29, v29, v29
	v_add3_u32 v55, v38, v192, v27
	ds_write_b16 v55, v29 offset:10496
	v_fma_f32 v29, v56, v18, v215
	v_cvt_pk_bf16_f32 v29, v29, v29
	v_add3_u32 v56, v38, v190, v27
	ds_write_b16 v56, v29 offset:10752
	v_fma_f32 v29, v54, v18, v215
	v_cvt_pk_bf16_f32 v29, v29, v29
	v_add3_u32 v54, v38, v189, v27
	ds_write_b16 v54, v29 offset:11008
	v_fma_f32 v29, v53, v18, v215
	v_cvt_pk_bf16_f32 v29, v29, v29
	v_add3_u32 v53, v38, v188, v27
	ds_write_b16 v53, v29 offset:11264
	v_fma_f32 v29, v51, v18, v215
	v_cvt_pk_bf16_f32 v29, v29, v29
	v_add3_u32 v51, v38, v187, v27
	ds_write_b16 v51, v29 offset:11520
	v_fma_f32 v29, v49, v18, v215
	v_cvt_pk_bf16_f32 v29, v29, v29
	v_add3_u32 v49, v38, v184, v27
	ds_write_b16 v49, v29 offset:11776
	v_fma_f32 v29, v47, v18, v215
	v_cvt_pk_bf16_f32 v29, v29, v29
	v_add3_u32 v45, v38, v45, v27
	ds_write_b16 v45, v29 offset:12032
	v_fma_f32 v29, v52, v18, v215
	v_cvt_pk_bf16_f32 v29, v29, v29
	v_add3_u32 v46, v38, v46, v27
	ds_write_b16 v46, v29 offset:12288
	v_fma_f32 v29, v50, v18, v215
	v_cvt_pk_bf16_f32 v29, v29, v29
	v_add3_u32 v46, v38, v199, v27
	ds_write_b16 v46, v29 offset:12544
	v_fma_f32 v29, v48, v18, v215
	v_cvt_pk_bf16_f32 v29, v29, v29
	v_add3_u32 v46, v38, v198, v27
	ds_write_b16 v46, v29 offset:12800
	v_mul_f32_e32 v29, v37, v18
	v_bfe_u32 v36, v29, 16, 1
	v_add3_u32 v29, v29, v36, s15
	v_add3_u32 v36, v38, v197, v27
	ds_write_b16_d16_hi v36, v29 offset:13056
	v_fma_f32 v29, v34, v18, v215
	v_cvt_pk_bf16_f32 v29, v29, v29
	v_add3_u32 v34, v38, v196, v27
	ds_write_b16 v34, v29 offset:13312
	v_sub_f32_e32 v29, v24, v39
	v_pk_fma_f32 v[24:25], v[40:41], s[22:23], v[24:25] op_sel_hi:[1,0,1] neg_lo:[1,0,0] neg_hi:[1,0,0]
	v_mul_f32_e32 v29, v29, v18
	v_mul_f32_e32 v24, v25, v18
	v_bfe_u32 v34, v29, 16, 1
	v_bfe_u32 v25, v24, 16, 1
	v_add3_u32 v29, v29, v34, s15
	v_add3_u32 v34, v38, v195, v27
	v_add3_u32 v24, v24, v25, s15
	v_add3_u32 v25, v38, v193, v27
	ds_write_b16_d16_hi v34, v29 offset:13568
	ds_write_b16_d16_hi v25, v24 offset:13824
	v_pk_fma_f32 v[24:25], v[40:41], s[22:23], v[32:33] op_sel_hi:[1,0,1] neg_lo:[1,0,0] neg_hi:[1,0,0]
	v_and_b32_e32 v167, 15, v43
	v_mul_f32_e32 v24, v25, v18
	v_bfe_u32 v25, v24, 16, 1
	v_add3_u32 v24, v24, v25, s15
	v_add3_u32 v25, v38, v191, v27
	ds_write_b16_d16_hi v25, v24 offset:14080
	v_fma_f32 v24, v28, v18, v215
	v_cvt_pk_bf16_f32 v24, v24, v24
	ds_write_b16 v35, v24 offset:14336
	v_sub_f32_e32 v24, v22, v39
	v_pk_fma_f32 v[22:23], v[40:41], s[22:23], v[22:23] op_sel_hi:[1,0,1] neg_lo:[1,0,0] neg_hi:[1,0,0]
	v_mul_f32_e32 v24, v24, v18
	v_mul_f32_e32 v22, v23, v18
	v_bfe_u32 v25, v24, 16, 1
	v_bfe_u32 v23, v22, 16, 1
	v_add3_u32 v24, v24, v25, s15
	v_add3_u32 v22, v22, v23, s15
	ds_write_b16_d16_hi v55, v24 offset:14592
	ds_write_b16_d16_hi v56, v22 offset:14848
	v_pk_fma_f32 v[22:23], v[40:41], s[22:23], v[30:31] op_sel_hi:[1,0,1] neg_lo:[1,0,0] neg_hi:[1,0,0]
	s_nop 0
	v_mul_f32_e32 v22, v23, v18
	v_bfe_u32 v23, v22, 16, 1
	v_add3_u32 v22, v22, v23, s15
	ds_write_b16_d16_hi v54, v22 offset:15104
	v_fma_f32 v22, v26, v18, v215
	v_cvt_pk_bf16_f32 v22, v22, v22
	ds_write_b16 v53, v22 offset:15360
	v_sub_f32_e32 v22, v20, v39
	v_pk_fma_f32 v[20:21], v[40:41], s[22:23], v[20:21] op_sel_hi:[1,0,1] neg_lo:[1,0,0] neg_hi:[1,0,0]
	v_mul_f32_e32 v22, v22, v18
	v_mul_f32_e32 v20, v21, v18
	v_mul_f32_e32 v18, v19, v18
	v_bfe_u32 v23, v22, 16, 1
	v_bfe_u32 v21, v20, 16, 1
	v_bfe_u32 v19, v18, 16, 1
	v_add3_u32 v22, v22, v23, s15
	v_add3_u32 v20, v20, v21, s15
	v_add3_u32 v18, v18, v19, s15
	ds_write_b16_d16_hi v51, v22 offset:15616
	ds_write_b16_d16_hi v49, v20 offset:15872
	ds_write_b16_d16_hi v45, v18 offset:16128
	v_lshrrev_b32_e32 v18, 1, v43
	v_and_b32_e32 v18, 32, v18
	v_lshl_or_b32 v166, v44, 6, v18
	v_or_b32_e32 v18, v166, v168
	v_lshl_add_u32 v165, v18, 8, 32
	v_bitop3_b32 v18, v42, v167, 1 bitop3:0x6c
	v_lshl_add_u32 v18, v18, 4, v165
	s_waitcnt lgkmcnt(0)
	s_barrier
	ds_read_b128 v[170:173], v18 offset:55296
	s_waitcnt lgkmcnt(0)
	v_mfma_f32_32x32x16_bf16 v[50:65], v[170:173], v[2:5], 0
	v_mfma_f32_32x32x16_bf16 v[34:49], v[170:173], v[6:9], 0
	v_mfma_f32_32x32x16_bf16 v[18:33], v[170:173], v[10:13], 0
	v_mfma_f32_32x32x16_bf16 v[2:17], v[170:173], v[14:17], 0
	v_bitop3_b32 v170, v169, v167, 2 bitop3:0x36
	v_lshl_add_u32 v170, v170, 4, v165
	ds_read_b128 v[170:173], v170 offset:55296
	s_waitcnt lgkmcnt(0)
	v_mfma_f32_32x32x16_bf16 v[50:65], v[170:173], v[138:141], v[50:65]
	v_bitop3_b32 v138, v169, v167, 4 bitop3:0x36
	v_lshl_add_u32 v138, v138, 4, v165
	ds_read_b128 v[138:141], v138 offset:55296
	v_mfma_f32_32x32x16_bf16 v[34:49], v[170:173], v[142:145], v[34:49]
	v_mfma_f32_32x32x16_bf16 v[18:33], v[170:173], v[146:149], v[18:33]
	s_waitcnt lgkmcnt(0)
	v_mfma_f32_32x32x16_bf16 v[34:49], v[138:141], v[126:129], v[34:49]
	v_bitop3_b32 v126, v169, v167, 6 bitop3:0x36
	v_lshl_add_u32 v126, v126, 4, v165
	ds_read_b128 v[126:129], v126 offset:55296
	v_mfma_f32_32x32x16_bf16 v[2:17], v[170:173], v[150:153], v[2:17]
	v_mfma_f32_32x32x16_bf16 v[18:33], v[138:141], v[130:133], v[18:33]
	s_waitcnt lgkmcnt(0)
	v_mfma_f32_32x32x16_bf16 v[34:49], v[126:129], v[114:117], v[34:49]
	v_bitop3_b32 v114, v169, v167, 8 bitop3:0x36
	v_lshl_add_u32 v114, v114, 4, v165
	ds_read_b128 v[114:117], v114 offset:55296
	v_mfma_f32_32x32x16_bf16 v[2:17], v[138:141], v[134:137], v[2:17]
	v_mfma_f32_32x32x16_bf16 v[18:33], v[126:129], v[118:121], v[18:33]
	v_mfma_f32_32x32x16_bf16 v[2:17], v[126:129], v[122:125], v[2:17]
	v_lshlrev_b32_e32 v128, 7, v164
	v_or_b32_e32 v126, v128, v168
	v_ashrrev_i32_e32 v127, 31, v126
	v_lshlrev_b64 v[130:131], 2, v[126:127]
	v_lshl_or_b32 v122, v169, 2, v166
	v_or_b32_e32 v124, s3, v168
	v_mov_b32_e32 v125, s5
	s_waitcnt lgkmcnt(0)
	v_mfma_f32_32x32x16_bf16 v[18:33], v[114:117], v[106:109], v[18:33]
	v_bitop3_b32 v106, v169, v167, 10 bitop3:0x36
	v_lshl_add_u32 v106, v106, 4, v165
	ds_read_b128 v[106:109], v106 offset:55296
	v_lshl_add_u64 v[132:133], s[6:7], 0, v[130:131]
	v_lshl_add_u64 v[130:131], s[92:93], 0, v[130:131]
	v_ashrrev_i32_e32 v123, 31, v122
	v_lshlrev_b64 v[122:123], 1, v[122:123]
	v_mfma_f32_32x32x16_bf16 v[2:17], v[114:117], v[110:113], v[2:17]
	s_add_i32 s3, s3, s18
	s_cmpk_gt_i32 s4, 0x7f
	s_waitcnt lgkmcnt(0)
	v_mfma_f32_32x32x16_bf16 v[18:33], v[106:109], v[98:101], v[18:33]
	v_bitop3_b32 v98, v169, v167, 12 bitop3:0x36
	v_lshl_add_u32 v98, v98, 4, v165
	ds_read_b128 v[98:101], v98 offset:55296
	v_mfma_f32_32x32x16_bf16 v[2:17], v[106:109], v[102:105], v[2:17]
	s_waitcnt lgkmcnt(0)
	v_mfma_f32_32x32x16_bf16 v[2:17], v[98:101], v[94:97], v[2:17]
	v_bitop3_b32 v94, v169, v167, 14 bitop3:0x36
	v_lshl_add_u32 v94, v94, 4, v165
	ds_read_b128 v[94:97], v94 offset:55296
	v_ashrrev_i32_e32 v167, 31, v166
	s_waitcnt lgkmcnt(0)
	v_mfma_f32_32x32x16_bf16 v[2:17], v[94:97], v[90:93], v[2:17]
	v_lshlrev_b64 v[90:91], 2, v[166:167]
	v_lshl_add_u64 v[92:93], s[10:11], 0, v[90:91]
	v_lshl_add_u64 v[90:91], s[40:41], 0, v[90:91]
	v_lshl_add_u64 v[92:93], v[92:93], 0, v[154:155]
	v_lshl_add_u64 v[94:95], v[90:91], 0, v[154:155]
	global_load_dwordx4 v[114:117], v[92:93], off
	global_load_dwordx4 v[118:121], v[94:95], off
	global_load_dwordx4 v[106:109], v[92:93], off offset:32
	global_load_dwordx4 v[110:113], v[94:95], off offset:32
	global_load_dwordx4 v[98:101], v[92:93], off offset:64
	global_load_dwordx4 v[102:105], v[94:95], off offset:64
	s_nop 0
	global_load_dwordx4 v[90:93], v[92:93], off offset:96
	s_nop 0
	global_load_dwordx4 v[94:97], v[94:95], off offset:96
	s_nop 0
	global_load_dword v186, v[132:133], off
	global_load_dword v187, v[132:133], off offset:128
	global_load_dword v188, v[132:133], off offset:256
	global_load_dword v189, v[132:133], off offset:384
	global_load_dword v190, v[130:131], off
	global_load_dword v191, v[130:131], off offset:128
	global_load_dword v192, v[130:131], off offset:256
	global_load_dword v193, v[130:131], off offset:384
	v_lshlrev_b64 v[176:177], 11, v[124:125]
	v_lshl_add_u64 v[176:177], s[62:63], 0, v[176:177]
	v_lshl_add_u64 v[176:177], v[176:177], 0, v[122:123]
	v_add_co_u32_e32 v178, vcc, 0x10000, v176
	s_nop 1
	v_addc_co_u32_e32 v179, vcc, 0, v177, vcc
	v_add_co_u32_e32 v182, vcc, 0x20000, v176
	s_nop 1
	v_addc_co_u32_e32 v183, vcc, 0, v177, vcc
	v_add_co_u32_e32 v184, vcc, 0x30000, v176
	s_nop 1
	v_addc_co_u32_e32 v185, vcc, 0, v177, vcc
	s_waitcnt vmcnt(0)
	v_mul_f32_e32 v194, v118, v186
	v_fmac_f32_e32 v194, v50, v114
	v_add_f32_e32 v50, v190, v194
	v_lshlrev_b32_e32 v195, 16, v216
	v_mul_f32_e32 v50, v50, v195
	v_mul_f32_e32 v194, v119, v186
	v_fmac_f32_e32 v194, v51, v115
	v_add_f32_e32 v51, v190, v194
	v_and_b32_e32 v195, 0xffff0000, v216
	v_mul_f32_e32 v51, v51, v195
	v_mul_f32_e32 v194, v120, v186
	v_fmac_f32_e32 v194, v52, v116
	v_add_f32_e32 v52, v190, v194
	v_lshlrev_b32_e32 v195, 16, v217
	v_mul_f32_e32 v52, v52, v195
	v_mul_f32_e32 v194, v121, v186
	v_fmac_f32_e32 v194, v53, v117
	v_add_f32_e32 v53, v190, v194
	v_and_b32_e32 v195, 0xffff0000, v217
	v_mul_f32_e32 v53, v53, v195
	v_cvt_pk_bf16_f32 v50, v50, v51
	v_cvt_pk_bf16_f32 v51, v52, v53
	global_store_dwordx2 v[176:177], v[50:51], off offset:1536
	v_mul_f32_e32 v194, v110, v186
	v_fmac_f32_e32 v194, v54, v106
	v_add_f32_e32 v54, v190, v194
	v_lshlrev_b32_e32 v195, 16, v218
	v_mul_f32_e32 v54, v54, v195
	v_mul_f32_e32 v194, v111, v186
	v_fmac_f32_e32 v194, v55, v107
	v_add_f32_e32 v55, v190, v194
	v_and_b32_e32 v195, 0xffff0000, v218
	v_mul_f32_e32 v55, v55, v195
	v_mul_f32_e32 v194, v112, v186
	v_fmac_f32_e32 v194, v56, v108
	v_add_f32_e32 v56, v190, v194
	v_lshlrev_b32_e32 v195, 16, v219
	v_mul_f32_e32 v56, v56, v195
	v_mul_f32_e32 v194, v113, v186
	v_fmac_f32_e32 v194, v57, v109
	v_add_f32_e32 v57, v190, v194
	v_and_b32_e32 v195, 0xffff0000, v219
	v_mul_f32_e32 v57, v57, v195
	v_cvt_pk_bf16_f32 v54, v54, v55
	v_cvt_pk_bf16_f32 v55, v56, v57
	global_store_dwordx2 v[176:177], v[54:55], off offset:1552
	v_mul_f32_e32 v194, v102, v186
	v_fmac_f32_e32 v194, v58, v98
	v_add_f32_e32 v58, v190, v194
	v_lshlrev_b32_e32 v195, 16, v220
	v_mul_f32_e32 v58, v58, v195
	v_mul_f32_e32 v194, v103, v186
	v_fmac_f32_e32 v194, v59, v99
	v_add_f32_e32 v59, v190, v194
	v_and_b32_e32 v195, 0xffff0000, v220
	v_mul_f32_e32 v59, v59, v195
	v_mul_f32_e32 v194, v104, v186
	v_fmac_f32_e32 v194, v60, v100
	v_add_f32_e32 v60, v190, v194
	v_lshlrev_b32_e32 v195, 16, v221
	v_mul_f32_e32 v60, v60, v195
	v_mul_f32_e32 v194, v105, v186
	v_fmac_f32_e32 v194, v61, v101
	v_add_f32_e32 v61, v190, v194
	v_and_b32_e32 v195, 0xffff0000, v221
	v_mul_f32_e32 v61, v61, v195
	v_cvt_pk_bf16_f32 v58, v58, v59
	v_cvt_pk_bf16_f32 v59, v60, v61
	global_store_dwordx2 v[176:177], v[58:59], off offset:1568
	v_mul_f32_e32 v194, v94, v186
	v_fmac_f32_e32 v194, v62, v90
	v_add_f32_e32 v62, v190, v194
	v_lshlrev_b32_e32 v195, 16, v222
	v_mul_f32_e32 v62, v62, v195
	v_mul_f32_e32 v194, v95, v186
	v_fmac_f32_e32 v194, v63, v91
	v_add_f32_e32 v63, v190, v194
	v_and_b32_e32 v195, 0xffff0000, v222
	v_mul_f32_e32 v63, v63, v195
	v_mul_f32_e32 v194, v96, v186
	v_fmac_f32_e32 v194, v64, v92
	v_add_f32_e32 v64, v190, v194
	v_lshlrev_b32_e32 v195, 16, v223
	v_mul_f32_e32 v64, v64, v195
	v_mul_f32_e32 v194, v97, v186
	v_fmac_f32_e32 v194, v65, v93
	v_add_f32_e32 v65, v190, v194
	v_and_b32_e32 v195, 0xffff0000, v223
	v_mul_f32_e32 v65, v65, v195
	v_cvt_pk_bf16_f32 v62, v62, v63
	v_cvt_pk_bf16_f32 v63, v64, v65
	global_store_dwordx2 v[176:177], v[62:63], off offset:1584
	v_mul_f32_e32 v194, v118, v187
	v_fmac_f32_e32 v194, v34, v114
	v_add_f32_e32 v34, v191, v194
	v_lshlrev_b32_e32 v195, 16, v224
	v_mul_f32_e32 v34, v34, v195
	v_mul_f32_e32 v194, v119, v187
	v_fmac_f32_e32 v194, v35, v115
	v_add_f32_e32 v35, v191, v194
	v_and_b32_e32 v195, 0xffff0000, v224
	v_mul_f32_e32 v35, v35, v195
	v_mul_f32_e32 v194, v120, v187
	v_fmac_f32_e32 v194, v36, v116
	v_add_f32_e32 v36, v191, v194
	v_lshlrev_b32_e32 v195, 16, v225
	v_mul_f32_e32 v36, v36, v195
	v_mul_f32_e32 v194, v121, v187
	v_fmac_f32_e32 v194, v37, v117
	v_add_f32_e32 v37, v191, v194
	v_and_b32_e32 v195, 0xffff0000, v225
	v_mul_f32_e32 v37, v37, v195
	v_cvt_pk_bf16_f32 v34, v34, v35
	v_cvt_pk_bf16_f32 v35, v36, v37
	global_store_dwordx2 v[178:179], v[34:35], off offset:1536
	v_mul_f32_e32 v194, v110, v187
	v_fmac_f32_e32 v194, v38, v106
	v_add_f32_e32 v38, v191, v194
	v_lshlrev_b32_e32 v195, 16, v226
	v_mul_f32_e32 v38, v38, v195
	v_mul_f32_e32 v194, v111, v187
	v_fmac_f32_e32 v194, v39, v107
	v_add_f32_e32 v39, v191, v194
	v_and_b32_e32 v195, 0xffff0000, v226
	v_mul_f32_e32 v39, v39, v195
	v_mul_f32_e32 v194, v112, v187
	v_fmac_f32_e32 v194, v40, v108
	v_add_f32_e32 v40, v191, v194
	v_lshlrev_b32_e32 v195, 16, v227
	v_mul_f32_e32 v40, v40, v195
	v_mul_f32_e32 v194, v113, v187
	v_fmac_f32_e32 v194, v41, v109
	v_add_f32_e32 v41, v191, v194
	v_and_b32_e32 v195, 0xffff0000, v227
	v_mul_f32_e32 v41, v41, v195
	v_cvt_pk_bf16_f32 v38, v38, v39
	v_cvt_pk_bf16_f32 v39, v40, v41
	global_store_dwordx2 v[178:179], v[38:39], off offset:1552
	v_mul_f32_e32 v194, v102, v187
	v_fmac_f32_e32 v194, v42, v98
	v_add_f32_e32 v42, v191, v194
	v_lshlrev_b32_e32 v195, 16, v228
	v_mul_f32_e32 v42, v42, v195
	v_mul_f32_e32 v194, v103, v187
	v_fmac_f32_e32 v194, v43, v99
	v_add_f32_e32 v43, v191, v194
	v_and_b32_e32 v195, 0xffff0000, v228
	v_mul_f32_e32 v43, v43, v195
	v_mul_f32_e32 v194, v104, v187
	v_fmac_f32_e32 v194, v44, v100
	v_add_f32_e32 v44, v191, v194
	v_lshlrev_b32_e32 v195, 16, v229
	v_mul_f32_e32 v44, v44, v195
	v_mul_f32_e32 v194, v105, v187
	v_fmac_f32_e32 v194, v45, v101
	v_add_f32_e32 v45, v191, v194
	v_and_b32_e32 v195, 0xffff0000, v229
	v_mul_f32_e32 v45, v45, v195
	v_cvt_pk_bf16_f32 v42, v42, v43
	v_cvt_pk_bf16_f32 v43, v44, v45
	global_store_dwordx2 v[178:179], v[42:43], off offset:1568
	v_mul_f32_e32 v194, v94, v187
	v_fmac_f32_e32 v194, v46, v90
	v_add_f32_e32 v46, v191, v194
	v_lshlrev_b32_e32 v195, 16, v230
	v_mul_f32_e32 v46, v46, v195
	v_mul_f32_e32 v194, v95, v187
	v_fmac_f32_e32 v194, v47, v91
	v_add_f32_e32 v47, v191, v194
	v_and_b32_e32 v195, 0xffff0000, v230
	v_mul_f32_e32 v47, v47, v195
	v_mul_f32_e32 v194, v96, v187
	v_fmac_f32_e32 v194, v48, v92
	v_add_f32_e32 v48, v191, v194
	v_lshlrev_b32_e32 v195, 16, v231
	v_mul_f32_e32 v48, v48, v195
	v_mul_f32_e32 v194, v97, v187
	v_fmac_f32_e32 v194, v49, v93
	v_add_f32_e32 v49, v191, v194
	v_and_b32_e32 v195, 0xffff0000, v231
	v_mul_f32_e32 v49, v49, v195
	v_cvt_pk_bf16_f32 v46, v46, v47
	v_cvt_pk_bf16_f32 v47, v48, v49
	global_store_dwordx2 v[178:179], v[46:47], off offset:1584
	v_mul_f32_e32 v194, v118, v188
	v_fmac_f32_e32 v194, v18, v114
	v_add_f32_e32 v18, v192, v194
	v_lshlrev_b32_e32 v195, 16, v232
	v_mul_f32_e32 v18, v18, v195
	v_mul_f32_e32 v194, v119, v188
	v_fmac_f32_e32 v194, v19, v115
	v_add_f32_e32 v19, v192, v194
	v_and_b32_e32 v195, 0xffff0000, v232
	v_mul_f32_e32 v19, v19, v195
	v_mul_f32_e32 v194, v120, v188
	v_fmac_f32_e32 v194, v20, v116
	v_add_f32_e32 v20, v192, v194
	v_lshlrev_b32_e32 v195, 16, v233
	v_mul_f32_e32 v20, v20, v195
	v_mul_f32_e32 v194, v121, v188
	v_fmac_f32_e32 v194, v21, v117
	v_add_f32_e32 v21, v192, v194
	v_and_b32_e32 v195, 0xffff0000, v233
	v_mul_f32_e32 v21, v21, v195
	v_cvt_pk_bf16_f32 v18, v18, v19
	v_cvt_pk_bf16_f32 v19, v20, v21
	global_store_dwordx2 v[182:183], v[18:19], off offset:1536
	v_mul_f32_e32 v194, v110, v188
	v_fmac_f32_e32 v194, v22, v106
	v_add_f32_e32 v22, v192, v194
	v_lshlrev_b32_e32 v195, 16, v234
	v_mul_f32_e32 v22, v22, v195
	v_mul_f32_e32 v194, v111, v188
	v_fmac_f32_e32 v194, v23, v107
	v_add_f32_e32 v23, v192, v194
	v_and_b32_e32 v195, 0xffff0000, v234
	v_mul_f32_e32 v23, v23, v195
	v_mul_f32_e32 v194, v112, v188
	v_fmac_f32_e32 v194, v24, v108
	v_add_f32_e32 v24, v192, v194
	v_lshlrev_b32_e32 v195, 16, v235
	v_mul_f32_e32 v24, v24, v195
	v_mul_f32_e32 v194, v113, v188
	v_fmac_f32_e32 v194, v25, v109
	v_add_f32_e32 v25, v192, v194
	v_and_b32_e32 v195, 0xffff0000, v235
	v_mul_f32_e32 v25, v25, v195
	v_cvt_pk_bf16_f32 v22, v22, v23
	v_cvt_pk_bf16_f32 v23, v24, v25
	global_store_dwordx2 v[182:183], v[22:23], off offset:1552
	v_mul_f32_e32 v194, v102, v188
	v_fmac_f32_e32 v194, v26, v98
	v_add_f32_e32 v26, v192, v194
	v_lshlrev_b32_e32 v195, 16, v236
	v_mul_f32_e32 v26, v26, v195
	v_mul_f32_e32 v194, v103, v188
	v_fmac_f32_e32 v194, v27, v99
	v_add_f32_e32 v27, v192, v194
	v_and_b32_e32 v195, 0xffff0000, v236
	v_mul_f32_e32 v27, v27, v195
	v_mul_f32_e32 v194, v104, v188
	v_fmac_f32_e32 v194, v28, v100
	v_add_f32_e32 v28, v192, v194
	v_lshlrev_b32_e32 v195, 16, v237
	v_mul_f32_e32 v28, v28, v195
	v_mul_f32_e32 v194, v105, v188
	v_fmac_f32_e32 v194, v29, v101
	v_add_f32_e32 v29, v192, v194
	v_and_b32_e32 v195, 0xffff0000, v237
	v_mul_f32_e32 v29, v29, v195
	v_cvt_pk_bf16_f32 v26, v26, v27
	v_cvt_pk_bf16_f32 v27, v28, v29
	global_store_dwordx2 v[182:183], v[26:27], off offset:1568
	v_mul_f32_e32 v194, v94, v188
	v_fmac_f32_e32 v194, v30, v90
	v_add_f32_e32 v30, v192, v194
	v_lshlrev_b32_e32 v195, 16, v238
	v_mul_f32_e32 v30, v30, v195
	v_mul_f32_e32 v194, v95, v188
	v_fmac_f32_e32 v194, v31, v91
	v_add_f32_e32 v31, v192, v194
	v_and_b32_e32 v195, 0xffff0000, v238
	v_mul_f32_e32 v31, v31, v195
	v_mul_f32_e32 v194, v96, v188
	v_fmac_f32_e32 v194, v32, v92
	v_add_f32_e32 v32, v192, v194
	v_lshlrev_b32_e32 v195, 16, v239
	v_mul_f32_e32 v32, v32, v195
	v_mul_f32_e32 v194, v97, v188
	v_fmac_f32_e32 v194, v33, v93
	v_add_f32_e32 v33, v192, v194
	v_and_b32_e32 v195, 0xffff0000, v239
	v_mul_f32_e32 v33, v33, v195
	v_cvt_pk_bf16_f32 v30, v30, v31
	v_cvt_pk_bf16_f32 v31, v32, v33
	global_store_dwordx2 v[182:183], v[30:31], off offset:1584
	v_mul_f32_e32 v194, v118, v189
	v_fmac_f32_e32 v194, v2, v114
	v_add_f32_e32 v2, v193, v194
	v_lshlrev_b32_e32 v195, 16, v240
	v_mul_f32_e32 v2, v2, v195
	v_mul_f32_e32 v194, v119, v189
	v_fmac_f32_e32 v194, v3, v115
	v_add_f32_e32 v3, v193, v194
	v_and_b32_e32 v195, 0xffff0000, v240
	v_mul_f32_e32 v3, v3, v195
	v_mul_f32_e32 v194, v120, v189
	v_fmac_f32_e32 v194, v4, v116
	v_add_f32_e32 v4, v193, v194
	v_lshlrev_b32_e32 v195, 16, v241
	v_mul_f32_e32 v4, v4, v195
	v_mul_f32_e32 v194, v121, v189
	v_fmac_f32_e32 v194, v5, v117
	v_add_f32_e32 v5, v193, v194
	v_and_b32_e32 v195, 0xffff0000, v241
	v_mul_f32_e32 v5, v5, v195
	v_cvt_pk_bf16_f32 v2, v2, v3
	v_cvt_pk_bf16_f32 v3, v4, v5
	global_store_dwordx2 v[184:185], v[2:3], off offset:1536
	v_mul_f32_e32 v194, v110, v189
	v_fmac_f32_e32 v194, v6, v106
	v_add_f32_e32 v6, v193, v194
	v_lshlrev_b32_e32 v195, 16, v246
	v_mul_f32_e32 v6, v6, v195
	v_mul_f32_e32 v194, v111, v189
	v_fmac_f32_e32 v194, v7, v107
	v_add_f32_e32 v7, v193, v194
	v_and_b32_e32 v195, 0xffff0000, v246
	v_mul_f32_e32 v7, v7, v195
	v_mul_f32_e32 v194, v112, v189
	v_fmac_f32_e32 v194, v8, v108
	v_add_f32_e32 v8, v193, v194
	v_lshlrev_b32_e32 v195, 16, v247
	v_mul_f32_e32 v8, v8, v195
	v_mul_f32_e32 v194, v113, v189
	v_fmac_f32_e32 v194, v9, v109
	v_add_f32_e32 v9, v193, v194
	v_and_b32_e32 v195, 0xffff0000, v247
	v_mul_f32_e32 v9, v9, v195
	v_cvt_pk_bf16_f32 v6, v6, v7
	v_cvt_pk_bf16_f32 v7, v8, v9
	global_store_dwordx2 v[184:185], v[6:7], off offset:1552
	v_mul_f32_e32 v194, v102, v189
	v_fmac_f32_e32 v194, v10, v98
	v_add_f32_e32 v10, v193, v194
	v_lshlrev_b32_e32 v195, 16, v252
	v_mul_f32_e32 v10, v10, v195
	v_mul_f32_e32 v194, v103, v189
	v_fmac_f32_e32 v194, v11, v99
	v_add_f32_e32 v11, v193, v194
	v_and_b32_e32 v195, 0xffff0000, v252
	v_mul_f32_e32 v11, v11, v195
	v_mul_f32_e32 v194, v104, v189
	v_fmac_f32_e32 v194, v12, v100
	v_add_f32_e32 v12, v193, v194
	v_lshlrev_b32_e32 v195, 16, v253
	v_mul_f32_e32 v12, v12, v195
	v_mul_f32_e32 v194, v105, v189
	v_fmac_f32_e32 v194, v13, v101
	v_add_f32_e32 v13, v193, v194
	v_and_b32_e32 v195, 0xffff0000, v253
	v_mul_f32_e32 v13, v13, v195
	v_cvt_pk_bf16_f32 v10, v10, v11
	v_cvt_pk_bf16_f32 v11, v12, v13
	global_store_dwordx2 v[184:185], v[10:11], off offset:1568
	v_mul_f32_e32 v194, v94, v189
	v_fmac_f32_e32 v194, v14, v90
	v_add_f32_e32 v14, v193, v194
	v_lshlrev_b32_e32 v195, 16, v254
	v_mul_f32_e32 v14, v14, v195
	v_mul_f32_e32 v194, v95, v189
	v_fmac_f32_e32 v194, v15, v91
	v_add_f32_e32 v15, v193, v194
	v_and_b32_e32 v195, 0xffff0000, v254
	v_mul_f32_e32 v15, v15, v195
	v_mul_f32_e32 v194, v96, v189
	v_fmac_f32_e32 v194, v16, v92
	v_add_f32_e32 v16, v193, v194
	v_lshlrev_b32_e32 v195, 16, v255
	v_mul_f32_e32 v16, v16, v195
	v_mul_f32_e32 v194, v97, v189
	v_fmac_f32_e32 v194, v17, v93
	v_add_f32_e32 v17, v193, v194
	v_and_b32_e32 v195, 0xffff0000, v255
	v_mul_f32_e32 v17, v17, v195
	v_cvt_pk_bf16_f32 v14, v14, v15
	v_cvt_pk_bf16_f32 v15, v16, v17
	global_store_dwordx2 v[184:185], v[14:15], off offset:1584
	s_barrier
	s_cbranch_scc0 .LBB0_779

.LBB0_849:
	v_mov_b32_e32 v43, v0
	s_ashr_i32 s5, s3, 31
	v_ashrrev_i32_e32 v44, 7, v43
	s_waitcnt vmcnt(7)
	v_add_u32_e32 v130, s2, v44
	v_ashrrev_i32_e32 v131, 31, v130
	v_and_b32_e32 v134, 31, v43
	s_waitcnt vmcnt(0)
	v_lshlrev_b64 v[2:3], 15, v[130:131]
	v_bfe_u32 v135, v43, 5, 1
	v_lshl_add_u64 v[2:3], s[56:57], 0, v[2:3]
	v_lshlrev_b32_e32 v154, 8, v134
	v_lshl_add_u64 v[2:3], v[2:3], 0, v[154:155]
	v_lshlrev_b32_e32 v154, 4, v135
	v_lshl_add_u64 v[18:19], v[2:3], 0, v[154:155]
	v_add_co_u32_e32 v20, vcc, s14, v18
	v_ashrrev_i32_e32 v45, 2, v43
	s_nop 0
	v_addc_co_u32_e32 v21, vcc, 0, v19, vcc
	v_add_co_u32_e32 v22, vcc, s17, v18
	global_load_dwordx4 v[2:5], v[18:19], off
	global_load_dwordx4 v[6:9], v[20:21], off
	v_addc_co_u32_e32 v23, vcc, 0, v19, vcc
	v_add_co_u32_e32 v24, vcc, s30, v18
	global_load_dwordx4 v[10:13], v[22:23], off
	s_nop 0
	v_addc_co_u32_e32 v25, vcc, 0, v19, vcc
	global_load_dwordx4 v[14:17], v[24:25], off
	global_load_dwordx4 v[114:117], v[18:19], off offset:32
	global_load_dwordx4 v[118:121], v[20:21], off offset:32
	global_load_dwordx4 v[122:125], v[22:23], off offset:32
	global_load_dwordx4 v[126:129], v[24:25], off offset:32
	global_load_dwordx4 v[102:105], v[20:21], off offset:64
	global_load_dwordx4 v[106:109], v[22:23], off offset:64
	global_load_dwordx4 v[110:113], v[24:25], off offset:64
	global_load_dwordx4 v[90:93], v[20:21], off offset:96
	global_load_dwordx4 v[94:97], v[22:23], off offset:96
	global_load_dwordx4 v[98:101], v[24:25], off offset:96
	global_load_dwordx4 v[82:85], v[22:23], off offset:128
	global_load_dwordx4 v[86:89], v[24:25], off offset:128
	global_load_dwordx4 v[74:77], v[22:23], off offset:160
	global_load_dwordx4 v[78:81], v[24:25], off offset:160
	global_load_dwordx4 v[70:73], v[24:25], off offset:192
	global_load_dwordx4 v[66:69], v[24:25], off offset:224
	v_add_u32_e32 v18, s3, v45
	v_ashrrev_i32_e32 v19, 31, v18
	v_lshlrev_b32_e32 v20, 6, v43
	v_lshlrev_b64 v[18:19], 12, v[18:19]
	v_and_b32_e32 v46, 0xc0, v20
	v_lshl_add_u64 v[18:19], s[60:61], 0, v[18:19]
	v_lshlrev_b32_e32 v20, 1, v46
	v_mov_b32_e32 v21, v155
	v_lshl_add_u64 v[34:35], v[18:19], 0, v[20:21]
	global_load_dwordx4 v[18:21], v[34:35], off offset:3632
	global_load_dwordx4 v[22:25], v[34:35], off offset:3616
	global_load_dwordx4 v[26:29], v[34:35], off offset:3600
	global_load_dwordx4 v[30:33], v[34:35], off offset:3584
	global_load_dwordx4 v[36:39], v[34:35], off offset:3680
	global_load_dwordx4 v[176:179], v[34:35], off offset:3664
	global_load_dwordx4 v[48:51], v[34:35], off offset:3648
	global_load_dwordx4 v[182:185], v[34:35], off offset:3696
	v_and_b32_e32 v215, 31, v0
	v_add_u32_e32 v215, s3, v215
	v_lshlrev_b32_e32 v215, 12, v215
	v_and_b32_e32 v245, 0x1c0, v0
	v_add_u32_e32 v215, v215, v245
	v_bfe_u32 v245, v0, 5, 1
	v_lshl_add_u32 v215, v245, 3, v215
	global_load_dwordx2 v[216:217], v215, s[60:61] offset:3072
	global_load_dwordx2 v[218:219], v215, s[60:61] offset:3088
	global_load_dwordx2 v[220:221], v215, s[60:61] offset:3104
	global_load_dwordx2 v[222:223], v215, s[60:61] offset:3120
	s_add_u32 s98, s60, 0x20000
	s_addc_u32 s99, s61, 0
	global_load_dwordx2 v[224:225], v215, s[98:99] offset:3072
	global_load_dwordx2 v[226:227], v215, s[98:99] offset:3088
	global_load_dwordx2 v[228:229], v215, s[98:99] offset:3104
	global_load_dwordx2 v[230:231], v215, s[98:99] offset:3120
	s_add_u32 s100, s60, 0x40000
	s_addc_u32 s101, s61, 0
	global_load_dwordx2 v[232:233], v215, s[100:101] offset:3072
	global_load_dwordx2 v[234:235], v215, s[100:101] offset:3088
	global_load_dwordx2 v[236:237], v215, s[100:101] offset:3104
	global_load_dwordx2 v[238:239], v215, s[100:101] offset:3120
	s_add_u32 s98, s60, 0x60000
	s_addc_u32 s99, s61, 0
	global_load_dwordx2 v[240:241], v215, s[98:99] offset:3072
	global_load_dwordx2 v[246:247], v215, s[98:99] offset:3088
	global_load_dwordx2 v[252:253], v215, s[98:99] offset:3104
	global_load_dwordx2 v[254:255], v215, s[98:99] offset:3120
	v_lshrrev_b32_e32 v42, 5, v43
	s_add_i32 s4, s4, s46
	s_waitcnt vmcnt(23)
	v_lshlrev_b32_e32 v144, 16, v18
	s_waitcnt vmcnt(22)
	v_lshlrev_b32_e32 v150, 16, v22
	s_waitcnt vmcnt(21)
	v_lshlrev_b32_e32 v168, 16, v26
	s_waitcnt vmcnt(20)
	v_lshlrev_b32_e32 v174, 16, v30
	v_and_b32_e32 v173, 0xffff0000, v30
	v_add_f32_e32 v30, 0, v174
	v_lshlrev_b32_e32 v172, 16, v31
	v_add_f32_e32 v30, v30, v173
	v_and_b32_e32 v171, 0xffff0000, v31
	v_mul_f32_e32 v31, v173, v173
	v_add_f32_e32 v30, v30, v172
	v_lshlrev_b32_e32 v170, 16, v32
	v_fmac_f32_e32 v31, v174, v174
	v_add_f32_e32 v30, v30, v171
	v_and_b32_e32 v169, 0xffff0000, v32
	v_fmac_f32_e32 v31, v172, v172
	v_add_f32_e32 v30, v30, v170
	v_lshlrev_b32_e32 v167, 16, v33
	v_fmac_f32_e32 v31, v171, v171
	v_add_f32_e32 v30, v30, v169
	v_and_b32_e32 v165, 0xffff0000, v33
	v_fmac_f32_e32 v31, v170, v170
	v_add_f32_e32 v30, v30, v167
	v_fmac_f32_e32 v31, v169, v169
	v_add_f32_e32 v30, v30, v165
	v_fmac_f32_e32 v31, v167, v167
	v_and_b32_e32 v166, 0xffff0000, v26
	v_add_f32_e32 v26, v30, v168
	v_fmac_f32_e32 v31, v165, v165
	v_lshlrev_b32_e32 v164, 16, v27
	v_add_f32_e32 v26, v26, v166
	v_and_b32_e32 v153, 0xffff0000, v27
	v_fmac_f32_e32 v31, v168, v168
	v_add_f32_e32 v26, v26, v164
	v_lshlrev_b32_e32 v152, 16, v28
	v_fmac_f32_e32 v31, v166, v166
	v_add_f32_e32 v26, v26, v153
	v_and_b32_e32 v151, 0xffff0000, v28
	v_fmac_f32_e32 v31, v164, v164
	v_add_f32_e32 v26, v26, v152
	v_lshlrev_b32_e32 v148, 16, v29
	v_fmac_f32_e32 v31, v153, v153
	v_add_f32_e32 v26, v26, v151
	v_and_b32_e32 v146, 0xffff0000, v29
	v_fmac_f32_e32 v31, v152, v152
	v_add_f32_e32 v26, v26, v148
	v_fmac_f32_e32 v31, v151, v151
	v_add_f32_e32 v26, v26, v146
	v_fmac_f32_e32 v31, v148, v148
	v_and_b32_e32 v149, 0xffff0000, v22
	v_add_f32_e32 v22, v26, v150
	v_fmac_f32_e32 v31, v146, v146
	v_lshlrev_b32_e32 v147, 16, v23
	v_add_f32_e32 v22, v22, v149
	v_and_b32_e32 v145, 0xffff0000, v23
	v_fmac_f32_e32 v31, v150, v150
	v_add_f32_e32 v22, v22, v147
	v_lshlrev_b32_e32 v143, 16, v24
	v_fmac_f32_e32 v31, v149, v149
	v_add_f32_e32 v22, v22, v145
	v_and_b32_e32 v141, 0xffff0000, v24
	v_fmac_f32_e32 v31, v147, v147
	v_add_f32_e32 v22, v22, v143
	v_lshlrev_b32_e32 v139, 16, v25
	v_fmac_f32_e32 v31, v145, v145
	v_add_f32_e32 v22, v22, v141
	v_and_b32_e32 v137, 0xffff0000, v25
	v_fmac_f32_e32 v31, v143, v143
	v_add_f32_e32 v22, v22, v139
	v_fmac_f32_e32 v31, v141, v141
	v_add_f32_e32 v22, v22, v137
	v_fmac_f32_e32 v31, v139, v139
	v_and_b32_e32 v142, 0xffff0000, v18
	v_add_f32_e32 v18, v22, v144
	v_fmac_f32_e32 v31, v137, v137
	v_lshlrev_b32_e32 v140, 16, v19
	v_add_f32_e32 v18, v18, v142
	v_and_b32_e32 v138, 0xffff0000, v19
	v_fmac_f32_e32 v31, v144, v144
	v_add_f32_e32 v18, v18, v140
	v_lshlrev_b32_e32 v133, 16, v20
	v_fmac_f32_e32 v31, v142, v142
	v_add_f32_e32 v18, v18, v138
	v_and_b32_e32 v131, 0xffff0000, v20
	v_fmac_f32_e32 v31, v140, v140
	v_add_f32_e32 v18, v18, v133
	v_lshlrev_b32_e32 v64, 16, v21
	v_fmac_f32_e32 v31, v138, v138
	v_add_f32_e32 v18, v18, v131
	v_and_b32_e32 v62, 0xffff0000, v21
	v_fmac_f32_e32 v31, v133, v133
	v_add_f32_e32 v18, v18, v64
	v_fmac_f32_e32 v31, v131, v131
	v_add_f32_e32 v18, v18, v62
	s_waitcnt vmcnt(17)
	v_lshlrev_b32_e32 v136, 16, v48
	v_fmac_f32_e32 v31, v64, v64
	v_and_b32_e32 v132, 0xffff0000, v48
	v_add_f32_e32 v18, v18, v136
	v_fmac_f32_e32 v31, v62, v62
	v_lshlrev_b32_e32 v65, 16, v49
	v_add_f32_e32 v18, v18, v132
	v_and_b32_e32 v63, 0xffff0000, v49
	v_fmac_f32_e32 v31, v136, v136
	v_add_f32_e32 v18, v18, v65
	v_lshlrev_b32_e32 v60, 16, v50
	v_fmac_f32_e32 v31, v132, v132
	v_add_f32_e32 v18, v18, v63
	v_and_b32_e32 v59, 0xffff0000, v50
	v_fmac_f32_e32 v31, v65, v65
	v_add_f32_e32 v18, v18, v60
	v_lshlrev_b32_e32 v57, 16, v51
	v_fmac_f32_e32 v31, v63, v63
	v_add_f32_e32 v18, v18, v59
	v_and_b32_e32 v55, 0xffff0000, v51
	v_fmac_f32_e32 v31, v60, v60
	v_add_f32_e32 v18, v18, v57
	v_fmac_f32_e32 v31, v59, v59
	v_add_f32_e32 v18, v18, v55
	v_lshlrev_b32_e32 v61, 16, v176
	v_fmac_f32_e32 v31, v57, v57
	v_and_b32_e32 v58, 0xffff0000, v176
	v_add_f32_e32 v18, v18, v61
	v_fmac_f32_e32 v31, v55, v55
	v_lshlrev_b32_e32 v56, 16, v177
	v_add_f32_e32 v18, v18, v58
	v_and_b32_e32 v54, 0xffff0000, v177
	v_fmac_f32_e32 v31, v61, v61
	v_add_f32_e32 v18, v18, v56
	v_lshlrev_b32_e32 v53, 16, v178
	v_fmac_f32_e32 v31, v58, v58
	v_add_f32_e32 v18, v18, v54
	v_and_b32_e32 v51, 0xffff0000, v178
	v_fmac_f32_e32 v31, v56, v56
	v_add_f32_e32 v18, v18, v53
	v_lshlrev_b32_e32 v49, 16, v179
	v_fmac_f32_e32 v31, v54, v54
	v_add_f32_e32 v18, v18, v51
	v_and_b32_e32 v47, 0xffff0000, v179
	v_fmac_f32_e32 v31, v53, v53
	v_add_f32_e32 v18, v18, v49
	v_fmac_f32_e32 v31, v51, v51
	v_add_f32_e32 v18, v18, v47
	v_lshlrev_b32_e32 v52, 16, v36
	v_fmac_f32_e32 v31, v49, v49
	v_and_b32_e32 v50, 0xffff0000, v36
	v_add_f32_e32 v18, v18, v52
	v_fmac_f32_e32 v31, v47, v47
	v_lshlrev_b32_e32 v48, 16, v37
	v_add_f32_e32 v18, v18, v50
	v_fmac_f32_e32 v31, v52, v52
	v_add_f32_e32 v18, v18, v48
	v_and_b32_e32 v37, 0xffff0000, v37
	v_fmac_f32_e32 v31, v50, v50
	v_lshlrev_b32_e32 v34, 16, v38
	v_mov_b32_e32 v35, v37
	v_add_f32_e32 v20, v18, v37
	v_fmac_f32_e32 v31, v48, v48
	v_and_b32_e32 v24, 0xffff0000, v38
	v_pk_mul_f32 v[18:19], v[34:35], v[34:35]
	v_add_f32_e32 v20, v20, v34
	v_lshlrev_b32_e32 v25, 16, v39
	v_add_f32_e32 v19, v19, v31
	v_add_f32_e32 v20, v20, v24
	v_add_f32_e32 v21, v18, v19
	v_pk_mul_f32 v[18:19], v[24:25], v[24:25]
	v_add_f32_e32 v20, v20, v25
	v_and_b32_e32 v33, 0xffff0000, v39
	v_add_f32_e32 v18, v18, v21
	s_waitcnt vmcnt(16)
	v_lshlrev_b32_e32 v28, 16, v182
	v_mov_b32_e32 v29, v33
	v_add_f32_e32 v20, v20, v33
	v_add_f32_e32 v21, v19, v18
	v_and_b32_e32 v22, 0xffff0000, v182
	v_pk_mul_f32 v[18:19], v[28:29], v[28:29]
	v_add_f32_e32 v20, v20, v28
	v_lshlrev_b32_e32 v23, 16, v183
	v_add_f32_e32 v19, v19, v21
	v_add_f32_e32 v20, v20, v22
	v_add_f32_e32 v21, v18, v19
	v_pk_mul_f32 v[18:19], v[22:23], v[22:23]
	v_add_f32_e32 v29, v20, v23
	v_and_b32_e32 v31, 0xffff0000, v183
	v_add_f32_e32 v18, v18, v21
	v_lshlrev_b32_e32 v26, 16, v184
	v_mov_b32_e32 v27, v31
	v_add_f32_e32 v29, v29, v31
	v_and_b32_e32 v36, s0, v38
	v_add_f32_e32 v18, v19, v18
	v_and_b32_e32 v20, 0xffff0000, v184
	v_pk_mul_f32 v[38:39], v[26:27], v[26:27]
	v_add_f32_e32 v27, v29, v26
	v_lshlrev_b32_e32 v21, 16, v185
	v_add_f32_e32 v18, v39, v18
	v_add_f32_e32 v27, v27, v20
	v_and_b32_e32 v29, 64, v181
	v_add_f32_e32 v18, v38, v18
	v_pk_mul_f32 v[40:41], v[20:21], v[20:21]
	v_add_f32_e32 v39, v27, v21
	v_xor_b32_e32 v27, 1, v181
	v_add_u32_e32 v29, 64, v29
	v_and_b32_e32 v19, 0xffff0000, v185
	v_add_f32_e32 v18, v40, v18
	v_cmp_lt_i32_e32 vcc, v27, v29
	v_add_f32_e32 v18, v41, v18
	v_mul_f32_e32 v38, v19, v19
	v_cndmask_b32_e32 v27, v181, v27, vcc
	v_lshlrev_b32_e32 v27, 2, v27
	v_pk_add_f32 v[38:39], v[38:39], v[18:19]
	ds_bpermute_b32 v41, v27, v39
	ds_bpermute_b32 v40, v27, v38
	v_xor_b32_e32 v35, 2, v181
	v_cmp_lt_i32_e32 vcc, v35, v29
	v_and_b32_e32 v30, s0, v182
	v_mov_b32_e32 v32, v36
	v_cndmask_b32_e32 v29, v181, v35, vcc
	v_lshlrev_b32_e32 v29, 2, v29
	s_waitcnt lgkmcnt(0)
	v_pk_add_f32 v[38:39], v[38:39], v[40:41]
	ds_bpermute_b32 v41, v29, v39
	ds_bpermute_b32 v40, v29, v38
	s_waitcnt lgkmcnt(0)
	v_pk_add_f32 v[40:41], v[38:39], v[40:41]
	s_nop 0
	v_pk_mul_f32 v[38:39], v[40:41], s[22:23] op_sel_hi:[1,0]
	v_pk_fma_f32 v[36:37], v[40:41], s[22:23], v[36:37] op_sel_hi:[1,0,1] neg_lo:[1,0,0] neg_hi:[1,0,0]
	v_fma_f32 v18, -v39, v39, v38
	v_max_f32_e32 v18, 0, v18
	v_add_f32_e32 v18, 0x358637bd, v18
	v_cmp_gt_f32_e32 vcc, s33, v18
	v_mul_f32_e32 v27, 0x4b800000, v18
	v_sub_f32_e32 v29, v174, v39
	v_cndmask_b32_e32 v18, v18, v27, vcc
	v_rsq_f32_e32 v18, v18
	v_sub_f32_e32 v19, v19, v39
	v_mul_f32_e32 v27, 0x45800000, v18
	v_cndmask_b32_e32 v18, v18, v27, vcc
	v_mul_f32_e32 v29, v29, v18
	v_lshlrev_b32_e32 v27, 1, v45
	v_bfe_u32 v35, v29, 16, 1
	v_ashrrev_i32_e32 v45, 1, v43
	v_and_b32_e32 v27, 14, v27
	v_add3_u32 v29, v29, v35, s15
	v_lshl_add_u32 v35, v46, 8, 32
	v_and_b32_e32 v46, -16, v45
	v_add3_u32 v174, v35, v46, v27
	ds_write_b16_d16_hi v174, v29 offset:55296
	v_mul_f32_e64 v215, -v39, v18
	v_fma_f32 v29, v173, v18, v215
	v_cvt_pk_bf16_f32 v29, v29, v29
	v_bitop3_b32 v173, v45, 16, -16 bitop3:0x6c
	v_add3_u32 v175, v35, v173, v27
	ds_write_b16 v175, v29 offset:55552
	v_fma_f32 v29, v172, v18, v215
	v_cvt_pk_bf16_f32 v29, v29, v29
	v_bitop3_b32 v172, v45, 32, -16 bitop3:0x6c
	v_add3_u32 v176, v35, v172, v27
	ds_write_b16 v176, v29 offset:55808
	v_fma_f32 v29, v171, v18, v215
	v_cvt_pk_bf16_f32 v29, v29, v29
	v_bitop3_b32 v171, v45, 48, -16 bitop3:0x6c
	v_add3_u32 v177, v35, v171, v27
	ds_write_b16 v177, v29 offset:56064
	v_fma_f32 v29, v170, v18, v215
	v_cvt_pk_bf16_f32 v29, v29, v29
	v_bitop3_b32 v170, v45, 64, -16 bitop3:0x6c
	v_add3_u32 v178, v35, v170, v27
	ds_write_b16 v178, v29 offset:56320
	v_fma_f32 v29, v169, v18, v215
	v_cvt_pk_bf16_f32 v29, v29, v29
	v_bitop3_b32 v169, v45, s34, -16 bitop3:0x6c
	v_add3_u32 v179, v35, v169, v27
	ds_write_b16 v179, v29 offset:56576
	v_fma_f32 v29, v167, v18, v215
	v_cvt_pk_bf16_f32 v29, v29, v29
	v_bitop3_b32 v167, v45, s31, -16 bitop3:0x6c
	v_add3_u32 v182, v35, v167, v27
	ds_write_b16 v182, v29 offset:56832
	v_fma_f32 v29, v165, v18, v215
	v_cvt_pk_bf16_f32 v29, v29, v29
	v_bitop3_b32 v165, v45, s13, -16 bitop3:0x6c
	v_add3_u32 v183, v35, v165, v27
	ds_write_b16 v183, v29 offset:57088
	v_fma_f32 v29, v168, v18, v215
	v_cvt_pk_bf16_f32 v29, v29, v29
	v_bitop3_b32 v168, v45, s12, -16 bitop3:0x6c
	v_add3_u32 v184, v35, v168, v27
	ds_write_b16 v184, v29 offset:57344
	v_fma_f32 v29, v166, v18, v215
	v_cvt_pk_bf16_f32 v29, v29, v29
	v_bitop3_b32 v166, v45, s35, -16 bitop3:0x6c
	v_add3_u32 v185, v35, v166, v27
	ds_write_b16 v185, v29 offset:57600
	v_fma_f32 v29, v164, v18, v215
	v_cvt_pk_bf16_f32 v29, v29, v29
	v_bitop3_b32 v164, v45, s38, -16 bitop3:0x6c
	v_add3_u32 v186, v35, v164, v27
	ds_write_b16 v186, v29 offset:57856
	v_fma_f32 v29, v153, v18, v215
	v_cvt_pk_bf16_f32 v29, v29, v29
	v_bitop3_b32 v153, v45, s39, -16 bitop3:0x6c
	v_add3_u32 v187, v35, v153, v27
	ds_write_b16 v187, v29 offset:58112
	v_fma_f32 v29, v152, v18, v215
	v_cvt_pk_bf16_f32 v29, v29, v29
	v_bitop3_b32 v152, v45, s16, -16 bitop3:0x6c
	v_add3_u32 v188, v35, v152, v27
	ds_write_b16 v188, v29 offset:58368
	v_fma_f32 v29, v151, v18, v215
	v_cvt_pk_bf16_f32 v29, v29, v29
	v_bitop3_b32 v151, v45, s40, -16 bitop3:0x6c
	v_add3_u32 v189, v35, v151, v27
	ds_write_b16 v189, v29 offset:58624
	v_fma_f32 v29, v148, v18, v215
	v_cvt_pk_bf16_f32 v29, v29, v29
	v_bitop3_b32 v148, v45, s41, -16 bitop3:0x6c
	v_add3_u32 v190, v35, v148, v27
	ds_write_b16 v190, v29 offset:58880
	v_sub_f32_e32 v29, v146, v39
	v_mul_f32_e32 v29, v29, v18
	v_bfe_u32 v146, v29, 16, 1
	v_bitop3_b32 v45, v45, s42, -16 bitop3:0x6c
	v_add_u32_e32 v38, 0xd800, v35
	v_add3_u32 v29, v29, v146, s15
	v_add3_u32 v35, v35, v45, v27
	ds_write_b16_d16_hi v35, v29 offset:59136
	v_fma_f32 v29, v150, v18, v215
	v_cvt_pk_bf16_f32 v29, v29, v29
	ds_write_b16 v174, v29 offset:59392
	v_fma_f32 v29, v149, v18, v215
	v_cvt_pk_bf16_f32 v29, v29, v29
	ds_write_b16 v175, v29 offset:59648
	v_fma_f32 v29, v147, v18, v215
	v_cvt_pk_bf16_f32 v29, v29, v29
	ds_write_b16 v176, v29 offset:59904
	v_fma_f32 v29, v145, v18, v215
	v_cvt_pk_bf16_f32 v29, v29, v29
	ds_write_b16 v177, v29 offset:60160
	v_fma_f32 v29, v143, v18, v215
	v_cvt_pk_bf16_f32 v29, v29, v29
	ds_write_b16 v178, v29 offset:60416
	v_fma_f32 v29, v141, v18, v215
	v_cvt_pk_bf16_f32 v29, v29, v29
	ds_write_b16 v179, v29 offset:60672
	v_fma_f32 v29, v139, v18, v215
	v_cvt_pk_bf16_f32 v29, v29, v29
	ds_write_b16 v182, v29 offset:60928
	v_fma_f32 v29, v137, v18, v215
	v_cvt_pk_bf16_f32 v29, v29, v29
	ds_write_b16 v183, v29 offset:61184
	v_fma_f32 v29, v144, v18, v215
	v_cvt_pk_bf16_f32 v29, v29, v29
	ds_write_b16 v184, v29 offset:61440
	v_fma_f32 v29, v142, v18, v215
	v_cvt_pk_bf16_f32 v29, v29, v29
	ds_write_b16 v185, v29 offset:61696
	v_fma_f32 v29, v140, v18, v215
	v_cvt_pk_bf16_f32 v29, v29, v29
	ds_write_b16 v186, v29 offset:61952
	v_fma_f32 v29, v138, v18, v215
	v_cvt_pk_bf16_f32 v29, v29, v29
	ds_write_b16 v187, v29 offset:62208
	v_fma_f32 v29, v133, v18, v215
	v_cvt_pk_bf16_f32 v29, v29, v29
	ds_write_b16 v188, v29 offset:62464
	v_fma_f32 v29, v131, v18, v215
	v_cvt_pk_bf16_f32 v29, v29, v29
	ds_write_b16 v189, v29 offset:62720
	v_fma_f32 v29, v64, v18, v215
	v_cvt_pk_bf16_f32 v29, v29, v29
	ds_write_b16 v190, v29 offset:62976
	v_fma_f32 v29, v62, v18, v215
	v_cvt_pk_bf16_f32 v29, v29, v29
	ds_write_b16 v35, v29 offset:63232
	v_fma_f32 v29, v136, v18, v215
	v_cvt_pk_bf16_f32 v29, v29, v29
	ds_write_b16 v174, v29 offset:63488
	v_fma_f32 v29, v132, v18, v215
	v_cvt_pk_bf16_f32 v29, v29, v29
	ds_write_b16 v175, v29 offset:63744
	v_fma_f32 v29, v65, v18, v215
	v_cvt_pk_bf16_f32 v29, v29, v29
	ds_write_b16 v176, v29 offset:64000
	v_fma_f32 v29, v63, v18, v215
	v_cvt_pk_bf16_f32 v29, v29, v29
	ds_write_b16 v177, v29 offset:64256
	v_fma_f32 v29, v60, v18, v215
	v_cvt_pk_bf16_f32 v29, v29, v29
	ds_write_b16 v178, v29 offset:64512
	v_fma_f32 v29, v59, v18, v215
	v_cvt_pk_bf16_f32 v29, v29, v29
	ds_write_b16 v179, v29 offset:64768
	v_fma_f32 v29, v57, v18, v215
	v_cvt_pk_bf16_f32 v29, v29, v29
	ds_write_b16 v182, v29 offset:65024
	v_fma_f32 v29, v55, v18, v215
	v_cvt_pk_bf16_f32 v29, v29, v29
	ds_write_b16 v183, v29 offset:65280
	v_fma_f32 v29, v61, v18, v215
	v_cvt_pk_bf16_f32 v29, v29, v29
	v_add3_u32 v35, v38, v168, v27
	ds_write_b16 v35, v29 offset:10240
	v_fma_f32 v29, v58, v18, v215
	v_cvt_pk_bf16_f32 v29, v29, v29
	v_add3_u32 v55, v38, v166, v27
	ds_write_b16 v55, v29 offset:10496
	v_fma_f32 v29, v56, v18, v215
	v_cvt_pk_bf16_f32 v29, v29, v29
	v_add3_u32 v56, v38, v164, v27
	ds_write_b16 v56, v29 offset:10752
	v_fma_f32 v29, v54, v18, v215
	v_cvt_pk_bf16_f32 v29, v29, v29
	v_add3_u32 v54, v38, v153, v27
	ds_write_b16 v54, v29 offset:11008
	v_fma_f32 v29, v53, v18, v215
	v_cvt_pk_bf16_f32 v29, v29, v29
	v_add3_u32 v53, v38, v152, v27
	ds_write_b16 v53, v29 offset:11264
	v_fma_f32 v29, v51, v18, v215
	v_cvt_pk_bf16_f32 v29, v29, v29
	v_add3_u32 v51, v38, v151, v27
	ds_write_b16 v51, v29 offset:11520
	v_fma_f32 v29, v49, v18, v215
	v_cvt_pk_bf16_f32 v29, v29, v29
	v_add3_u32 v49, v38, v148, v27
	ds_write_b16 v49, v29 offset:11776
	v_fma_f32 v29, v47, v18, v215
	v_cvt_pk_bf16_f32 v29, v29, v29
	v_add3_u32 v45, v38, v45, v27
	ds_write_b16 v45, v29 offset:12032
	v_fma_f32 v29, v52, v18, v215
	v_cvt_pk_bf16_f32 v29, v29, v29
	v_add3_u32 v46, v38, v46, v27
	ds_write_b16 v46, v29 offset:12288
	v_fma_f32 v29, v50, v18, v215
	v_cvt_pk_bf16_f32 v29, v29, v29
	v_add3_u32 v46, v38, v173, v27
	ds_write_b16 v46, v29 offset:12544
	v_fma_f32 v29, v48, v18, v215
	v_cvt_pk_bf16_f32 v29, v29, v29
	v_add3_u32 v46, v38, v172, v27
	ds_write_b16 v46, v29 offset:12800
	v_mul_f32_e32 v29, v37, v18
	v_bfe_u32 v36, v29, 16, 1
	v_add3_u32 v29, v29, v36, s15
	v_add3_u32 v36, v38, v171, v27
	ds_write_b16_d16_hi v36, v29 offset:13056
	v_fma_f32 v29, v34, v18, v215
	v_cvt_pk_bf16_f32 v29, v29, v29
	v_add3_u32 v34, v38, v170, v27
	ds_write_b16 v34, v29 offset:13312
	v_sub_f32_e32 v29, v24, v39
	v_pk_fma_f32 v[24:25], v[40:41], s[22:23], v[24:25] op_sel_hi:[1,0,1] neg_lo:[1,0,0] neg_hi:[1,0,0]
	v_mul_f32_e32 v29, v29, v18
	v_mul_f32_e32 v24, v25, v18
	v_bfe_u32 v34, v29, 16, 1
	v_bfe_u32 v25, v24, 16, 1
	v_add3_u32 v29, v29, v34, s15
	v_add3_u32 v34, v38, v169, v27
	v_add3_u32 v24, v24, v25, s15
	v_add3_u32 v25, v38, v167, v27
	ds_write_b16_d16_hi v34, v29 offset:13568
	ds_write_b16_d16_hi v25, v24 offset:13824
	v_pk_fma_f32 v[24:25], v[40:41], s[22:23], v[32:33] op_sel_hi:[1,0,1] neg_lo:[1,0,0] neg_hi:[1,0,0]
	v_and_b32_e32 v133, 15, v43
	v_mul_f32_e32 v24, v25, v18
	v_bfe_u32 v25, v24, 16, 1
	v_add3_u32 v24, v24, v25, s15
	v_add3_u32 v25, v38, v165, v27
	ds_write_b16_d16_hi v25, v24 offset:14080
	v_fma_f32 v24, v28, v18, v215
	v_cvt_pk_bf16_f32 v24, v24, v24
	ds_write_b16 v35, v24 offset:14336
	v_sub_f32_e32 v24, v22, v39
	v_pk_fma_f32 v[22:23], v[40:41], s[22:23], v[22:23] op_sel_hi:[1,0,1] neg_lo:[1,0,0] neg_hi:[1,0,0]
	v_mul_f32_e32 v24, v24, v18
	v_mul_f32_e32 v22, v23, v18
	v_bfe_u32 v25, v24, 16, 1
	v_bfe_u32 v23, v22, 16, 1
	v_add3_u32 v24, v24, v25, s15
	v_add3_u32 v22, v22, v23, s15
	ds_write_b16_d16_hi v55, v24 offset:14592
	ds_write_b16_d16_hi v56, v22 offset:14848
	v_pk_fma_f32 v[22:23], v[40:41], s[22:23], v[30:31] op_sel_hi:[1,0,1] neg_lo:[1,0,0] neg_hi:[1,0,0]
	s_nop 0
	v_mul_f32_e32 v22, v23, v18
	v_bfe_u32 v23, v22, 16, 1
	v_add3_u32 v22, v22, v23, s15
	ds_write_b16_d16_hi v54, v22 offset:15104
	v_fma_f32 v22, v26, v18, v215
	v_cvt_pk_bf16_f32 v22, v22, v22
	ds_write_b16 v53, v22 offset:15360
	v_sub_f32_e32 v22, v20, v39
	v_pk_fma_f32 v[20:21], v[40:41], s[22:23], v[20:21] op_sel_hi:[1,0,1] neg_lo:[1,0,0] neg_hi:[1,0,0]
	v_mul_f32_e32 v22, v22, v18
	v_mul_f32_e32 v20, v21, v18
	v_mul_f32_e32 v18, v19, v18
	v_bfe_u32 v23, v22, 16, 1
	v_bfe_u32 v21, v20, 16, 1
	v_bfe_u32 v19, v18, 16, 1
	v_add3_u32 v22, v22, v23, s15
	v_add3_u32 v20, v20, v21, s15
	v_add3_u32 v18, v18, v19, s15
	ds_write_b16_d16_hi v51, v22 offset:15616
	ds_write_b16_d16_hi v49, v20 offset:15872
	ds_write_b16_d16_hi v45, v18 offset:16128
	v_lshrrev_b32_e32 v18, 1, v43
	v_and_b32_e32 v18, 32, v18
	v_lshl_or_b32 v132, v44, 6, v18
	v_or_b32_e32 v18, v132, v134
	v_lshl_add_u32 v131, v18, 8, 32
	v_bitop3_b32 v18, v42, v133, 1 bitop3:0x6c
	v_lshl_add_u32 v18, v18, 4, v131
	s_waitcnt lgkmcnt(0)
	s_barrier
	ds_read_b128 v[136:139], v18 offset:55296
	s_waitcnt lgkmcnt(0)
	v_mfma_f32_32x32x16_bf16 v[50:65], v[136:139], v[2:5], 0
	v_mfma_f32_32x32x16_bf16 v[34:49], v[136:139], v[6:9], 0
	v_mfma_f32_32x32x16_bf16 v[18:33], v[136:139], v[10:13], 0
	v_mfma_f32_32x32x16_bf16 v[2:17], v[136:139], v[14:17], 0
	v_bitop3_b32 v136, v135, v133, 2 bitop3:0x36
	v_lshl_add_u32 v136, v136, 4, v131
	ds_read_b128 v[136:139], v136 offset:55296
	s_waitcnt lgkmcnt(0)
	v_mfma_f32_32x32x16_bf16 v[50:65], v[136:139], v[114:117], v[50:65]
	v_bitop3_b32 v114, v135, v133, 4 bitop3:0x36
	v_lshl_add_u32 v114, v114, 4, v131
	ds_read_b128 v[114:117], v114 offset:55296
	v_mfma_f32_32x32x16_bf16 v[34:49], v[136:139], v[118:121], v[34:49]
	v_mfma_f32_32x32x16_bf16 v[18:33], v[136:139], v[122:125], v[18:33]
	s_waitcnt lgkmcnt(0)
	v_mfma_f32_32x32x16_bf16 v[34:49], v[114:117], v[102:105], v[34:49]
	v_bitop3_b32 v102, v135, v133, 6 bitop3:0x36
	v_lshl_add_u32 v102, v102, 4, v131
	ds_read_b128 v[102:105], v102 offset:55296
	v_mfma_f32_32x32x16_bf16 v[2:17], v[136:139], v[126:129], v[2:17]
	v_mfma_f32_32x32x16_bf16 v[18:33], v[114:117], v[106:109], v[18:33]
	s_waitcnt lgkmcnt(0)
	v_mfma_f32_32x32x16_bf16 v[34:49], v[102:105], v[90:93], v[34:49]
	v_bitop3_b32 v90, v135, v133, 8 bitop3:0x36
	v_lshl_add_u32 v90, v90, 4, v131
	ds_read_b128 v[90:93], v90 offset:55296
	v_mfma_f32_32x32x16_bf16 v[2:17], v[114:117], v[110:113], v[2:17]
	v_mfma_f32_32x32x16_bf16 v[18:33], v[102:105], v[94:97], v[18:33]
	v_mfma_f32_32x32x16_bf16 v[2:17], v[102:105], v[98:101], v[2:17]
	v_lshlrev_b32_e32 v104, 7, v130
	v_or_b32_e32 v102, v104, v134
	v_ashrrev_i32_e32 v103, 31, v102
	v_lshlrev_b64 v[106:107], 2, v[102:103]
	v_lshl_or_b32 v98, v135, 2, v132
	v_or_b32_e32 v100, s3, v134
	v_mov_b32_e32 v101, s5
	s_waitcnt lgkmcnt(0)
	v_mfma_f32_32x32x16_bf16 v[18:33], v[90:93], v[82:85], v[18:33]
	v_bitop3_b32 v82, v135, v133, 10 bitop3:0x36
	v_lshl_add_u32 v82, v82, 4, v131
	ds_read_b128 v[82:85], v82 offset:55296
	v_lshl_add_u64 v[108:109], s[6:7], 0, v[106:107]
	v_lshl_add_u64 v[106:107], s[92:93], 0, v[106:107]
	v_ashrrev_i32_e32 v99, 31, v98
	v_lshlrev_b64 v[98:99], 1, v[98:99]
	v_mfma_f32_32x32x16_bf16 v[2:17], v[90:93], v[86:89], v[2:17]
	s_add_i32 s3, s3, s18
	s_cmpk_gt_i32 s4, 0x7f
	s_waitcnt lgkmcnt(0)
	v_mfma_f32_32x32x16_bf16 v[18:33], v[82:85], v[74:77], v[18:33]
	v_bitop3_b32 v74, v135, v133, 12 bitop3:0x36
	v_lshl_add_u32 v74, v74, 4, v131
	ds_read_b128 v[74:77], v74 offset:55296
	v_mfma_f32_32x32x16_bf16 v[2:17], v[82:85], v[78:81], v[2:17]
	s_waitcnt lgkmcnt(0)
	v_mfma_f32_32x32x16_bf16 v[2:17], v[74:77], v[70:73], v[2:17]
	v_bitop3_b32 v70, v135, v133, 14 bitop3:0x36
	v_lshl_add_u32 v70, v70, 4, v131
	ds_read_b128 v[70:73], v70 offset:55296
	v_ashrrev_i32_e32 v133, 31, v132
	s_waitcnt lgkmcnt(0)
	v_mfma_f32_32x32x16_bf16 v[2:17], v[70:73], v[66:69], v[2:17]
	v_lshlrev_b64 v[66:67], 2, v[132:133]
	v_lshl_add_u64 v[68:69], s[10:11], 0, v[66:67]
	v_lshl_add_u64 v[66:67], s[36:37], 0, v[66:67]
	v_lshl_add_u64 v[68:69], v[68:69], 0, v[154:155]
	v_lshl_add_u64 v[70:71], v[66:67], 0, v[154:155]
	global_load_dwordx4 v[90:93], v[68:69], off
	global_load_dwordx4 v[94:97], v[70:71], off
	global_load_dwordx4 v[82:85], v[68:69], off offset:32
	global_load_dwordx4 v[86:89], v[70:71], off offset:32
	global_load_dwordx4 v[74:77], v[68:69], off offset:64
	global_load_dwordx4 v[78:81], v[70:71], off offset:64
	s_nop 0
	global_load_dwordx4 v[66:69], v[68:69], off offset:96
	s_nop 0
	global_load_dwordx4 v[70:73], v[70:71], off offset:96
	s_nop 0
	global_load_dword v150, v[108:109], off
	global_load_dword v151, v[108:109], off offset:128
	global_load_dword v152, v[108:109], off offset:256
	global_load_dword v153, v[108:109], off offset:384
	global_load_dword v164, v[106:107], off
	global_load_dword v165, v[106:107], off offset:128
	global_load_dword v166, v[106:107], off offset:256
	global_load_dword v167, v[106:107], off offset:384
	v_lshlrev_b64 v[142:143], 11, v[100:101]
	v_lshl_add_u64 v[142:143], s[62:63], 0, v[142:143]
	v_lshl_add_u64 v[142:143], v[142:143], 0, v[98:99]
	v_add_co_u32_e32 v144, vcc, 0x10000, v142
	s_nop 1
	v_addc_co_u32_e32 v145, vcc, 0, v143, vcc
	v_add_co_u32_e32 v146, vcc, 0x20000, v142
	s_nop 1
	v_addc_co_u32_e32 v147, vcc, 0, v143, vcc
	v_add_co_u32_e32 v148, vcc, 0x30000, v142
	s_nop 1
	v_addc_co_u32_e32 v149, vcc, 0, v143, vcc
	s_waitcnt vmcnt(0)
	v_mul_f32_e32 v168, v94, v150
	v_fmac_f32_e32 v168, v50, v90
	v_add_f32_e32 v50, v164, v168
	v_lshlrev_b32_e32 v169, 16, v216
	v_mul_f32_e32 v50, v50, v169
	v_mul_f32_e32 v168, v95, v150
	v_fmac_f32_e32 v168, v51, v91
	v_add_f32_e32 v51, v164, v168
	v_and_b32_e32 v169, 0xffff0000, v216
	v_mul_f32_e32 v51, v51, v169
	v_mul_f32_e32 v168, v96, v150
	v_fmac_f32_e32 v168, v52, v92
	v_add_f32_e32 v52, v164, v168
	v_lshlrev_b32_e32 v169, 16, v217
	v_mul_f32_e32 v52, v52, v169
	v_mul_f32_e32 v168, v97, v150
	v_fmac_f32_e32 v168, v53, v93
	v_add_f32_e32 v53, v164, v168
	v_and_b32_e32 v169, 0xffff0000, v217
	v_mul_f32_e32 v53, v53, v169
	v_cvt_pk_bf16_f32 v50, v50, v51
	v_cvt_pk_bf16_f32 v51, v52, v53
	global_store_dwordx2 v[142:143], v[50:51], off offset:1536
	v_mul_f32_e32 v168, v86, v150
	v_fmac_f32_e32 v168, v54, v82
	v_add_f32_e32 v54, v164, v168
	v_lshlrev_b32_e32 v169, 16, v218
	v_mul_f32_e32 v54, v54, v169
	v_mul_f32_e32 v168, v87, v150
	v_fmac_f32_e32 v168, v55, v83
	v_add_f32_e32 v55, v164, v168
	v_and_b32_e32 v169, 0xffff0000, v218
	v_mul_f32_e32 v55, v55, v169
	v_mul_f32_e32 v168, v88, v150
	v_fmac_f32_e32 v168, v56, v84
	v_add_f32_e32 v56, v164, v168
	v_lshlrev_b32_e32 v169, 16, v219
	v_mul_f32_e32 v56, v56, v169
	v_mul_f32_e32 v168, v89, v150
	v_fmac_f32_e32 v168, v57, v85
	v_add_f32_e32 v57, v164, v168
	v_and_b32_e32 v169, 0xffff0000, v219
	v_mul_f32_e32 v57, v57, v169
	v_cvt_pk_bf16_f32 v54, v54, v55
	v_cvt_pk_bf16_f32 v55, v56, v57
	global_store_dwordx2 v[142:143], v[54:55], off offset:1552
	v_mul_f32_e32 v168, v78, v150
	v_fmac_f32_e32 v168, v58, v74
	v_add_f32_e32 v58, v164, v168
	v_lshlrev_b32_e32 v169, 16, v220
	v_mul_f32_e32 v58, v58, v169
	v_mul_f32_e32 v168, v79, v150
	v_fmac_f32_e32 v168, v59, v75
	v_add_f32_e32 v59, v164, v168
	v_and_b32_e32 v169, 0xffff0000, v220
	v_mul_f32_e32 v59, v59, v169
	v_mul_f32_e32 v168, v80, v150
	v_fmac_f32_e32 v168, v60, v76
	v_add_f32_e32 v60, v164, v168
	v_lshlrev_b32_e32 v169, 16, v221
	v_mul_f32_e32 v60, v60, v169
	v_mul_f32_e32 v168, v81, v150
	v_fmac_f32_e32 v168, v61, v77
	v_add_f32_e32 v61, v164, v168
	v_and_b32_e32 v169, 0xffff0000, v221
	v_mul_f32_e32 v61, v61, v169
	v_cvt_pk_bf16_f32 v58, v58, v59
	v_cvt_pk_bf16_f32 v59, v60, v61
	global_store_dwordx2 v[142:143], v[58:59], off offset:1568
	v_mul_f32_e32 v168, v70, v150
	v_fmac_f32_e32 v168, v62, v66
	v_add_f32_e32 v62, v164, v168
	v_lshlrev_b32_e32 v169, 16, v222
	v_mul_f32_e32 v62, v62, v169
	v_mul_f32_e32 v168, v71, v150
	v_fmac_f32_e32 v168, v63, v67
	v_add_f32_e32 v63, v164, v168
	v_and_b32_e32 v169, 0xffff0000, v222
	v_mul_f32_e32 v63, v63, v169
	v_mul_f32_e32 v168, v72, v150
	v_fmac_f32_e32 v168, v64, v68
	v_add_f32_e32 v64, v164, v168
	v_lshlrev_b32_e32 v169, 16, v223
	v_mul_f32_e32 v64, v64, v169
	v_mul_f32_e32 v168, v73, v150
	v_fmac_f32_e32 v168, v65, v69
	v_add_f32_e32 v65, v164, v168
	v_and_b32_e32 v169, 0xffff0000, v223
	v_mul_f32_e32 v65, v65, v169
	v_cvt_pk_bf16_f32 v62, v62, v63
	v_cvt_pk_bf16_f32 v63, v64, v65
	global_store_dwordx2 v[142:143], v[62:63], off offset:1584
	v_mul_f32_e32 v168, v94, v151
	v_fmac_f32_e32 v168, v34, v90
	v_add_f32_e32 v34, v165, v168
	v_lshlrev_b32_e32 v169, 16, v224
	v_mul_f32_e32 v34, v34, v169
	v_mul_f32_e32 v168, v95, v151
	v_fmac_f32_e32 v168, v35, v91
	v_add_f32_e32 v35, v165, v168
	v_and_b32_e32 v169, 0xffff0000, v224
	v_mul_f32_e32 v35, v35, v169
	v_mul_f32_e32 v168, v96, v151
	v_fmac_f32_e32 v168, v36, v92
	v_add_f32_e32 v36, v165, v168
	v_lshlrev_b32_e32 v169, 16, v225
	v_mul_f32_e32 v36, v36, v169
	v_mul_f32_e32 v168, v97, v151
	v_fmac_f32_e32 v168, v37, v93
	v_add_f32_e32 v37, v165, v168
	v_and_b32_e32 v169, 0xffff0000, v225
	v_mul_f32_e32 v37, v37, v169
	v_cvt_pk_bf16_f32 v34, v34, v35
	v_cvt_pk_bf16_f32 v35, v36, v37
	global_store_dwordx2 v[144:145], v[34:35], off offset:1536
	v_mul_f32_e32 v168, v86, v151
	v_fmac_f32_e32 v168, v38, v82
	v_add_f32_e32 v38, v165, v168
	v_lshlrev_b32_e32 v169, 16, v226
	v_mul_f32_e32 v38, v38, v169
	v_mul_f32_e32 v168, v87, v151
	v_fmac_f32_e32 v168, v39, v83
	v_add_f32_e32 v39, v165, v168
	v_and_b32_e32 v169, 0xffff0000, v226
	v_mul_f32_e32 v39, v39, v169
	v_mul_f32_e32 v168, v88, v151
	v_fmac_f32_e32 v168, v40, v84
	v_add_f32_e32 v40, v165, v168
	v_lshlrev_b32_e32 v169, 16, v227
	v_mul_f32_e32 v40, v40, v169
	v_mul_f32_e32 v168, v89, v151
	v_fmac_f32_e32 v168, v41, v85
	v_add_f32_e32 v41, v165, v168
	v_and_b32_e32 v169, 0xffff0000, v227
	v_mul_f32_e32 v41, v41, v169
	v_cvt_pk_bf16_f32 v38, v38, v39
	v_cvt_pk_bf16_f32 v39, v40, v41
	global_store_dwordx2 v[144:145], v[38:39], off offset:1552
	v_mul_f32_e32 v168, v78, v151
	v_fmac_f32_e32 v168, v42, v74
	v_add_f32_e32 v42, v165, v168
	v_lshlrev_b32_e32 v169, 16, v228
	v_mul_f32_e32 v42, v42, v169
	v_mul_f32_e32 v168, v79, v151
	v_fmac_f32_e32 v168, v43, v75
	v_add_f32_e32 v43, v165, v168
	v_and_b32_e32 v169, 0xffff0000, v228
	v_mul_f32_e32 v43, v43, v169
	v_mul_f32_e32 v168, v80, v151
	v_fmac_f32_e32 v168, v44, v76
	v_add_f32_e32 v44, v165, v168
	v_lshlrev_b32_e32 v169, 16, v229
	v_mul_f32_e32 v44, v44, v169
	v_mul_f32_e32 v168, v81, v151
	v_fmac_f32_e32 v168, v45, v77
	v_add_f32_e32 v45, v165, v168
	v_and_b32_e32 v169, 0xffff0000, v229
	v_mul_f32_e32 v45, v45, v169
	v_cvt_pk_bf16_f32 v42, v42, v43
	v_cvt_pk_bf16_f32 v43, v44, v45
	global_store_dwordx2 v[144:145], v[42:43], off offset:1568
	v_mul_f32_e32 v168, v70, v151
	v_fmac_f32_e32 v168, v46, v66
	v_add_f32_e32 v46, v165, v168
	v_lshlrev_b32_e32 v169, 16, v230
	v_mul_f32_e32 v46, v46, v169
	v_mul_f32_e32 v168, v71, v151
	v_fmac_f32_e32 v168, v47, v67
	v_add_f32_e32 v47, v165, v168
	v_and_b32_e32 v169, 0xffff0000, v230
	v_mul_f32_e32 v47, v47, v169
	v_mul_f32_e32 v168, v72, v151
	v_fmac_f32_e32 v168, v48, v68
	v_add_f32_e32 v48, v165, v168
	v_lshlrev_b32_e32 v169, 16, v231
	v_mul_f32_e32 v48, v48, v169
	v_mul_f32_e32 v168, v73, v151
	v_fmac_f32_e32 v168, v49, v69
	v_add_f32_e32 v49, v165, v168
	v_and_b32_e32 v169, 0xffff0000, v231
	v_mul_f32_e32 v49, v49, v169
	v_cvt_pk_bf16_f32 v46, v46, v47
	v_cvt_pk_bf16_f32 v47, v48, v49
	global_store_dwordx2 v[144:145], v[46:47], off offset:1584
	v_mul_f32_e32 v168, v94, v152
	v_fmac_f32_e32 v168, v18, v90
	v_add_f32_e32 v18, v166, v168
	v_lshlrev_b32_e32 v169, 16, v232
	v_mul_f32_e32 v18, v18, v169
	v_mul_f32_e32 v168, v95, v152
	v_fmac_f32_e32 v168, v19, v91
	v_add_f32_e32 v19, v166, v168
	v_and_b32_e32 v169, 0xffff0000, v232
	v_mul_f32_e32 v19, v19, v169
	v_mul_f32_e32 v168, v96, v152
	v_fmac_f32_e32 v168, v20, v92
	v_add_f32_e32 v20, v166, v168
	v_lshlrev_b32_e32 v169, 16, v233
	v_mul_f32_e32 v20, v20, v169
	v_mul_f32_e32 v168, v97, v152
	v_fmac_f32_e32 v168, v21, v93
	v_add_f32_e32 v21, v166, v168
	v_and_b32_e32 v169, 0xffff0000, v233
	v_mul_f32_e32 v21, v21, v169
	v_cvt_pk_bf16_f32 v18, v18, v19
	v_cvt_pk_bf16_f32 v19, v20, v21
	global_store_dwordx2 v[146:147], v[18:19], off offset:1536
	v_mul_f32_e32 v168, v86, v152
	v_fmac_f32_e32 v168, v22, v82
	v_add_f32_e32 v22, v166, v168
	v_lshlrev_b32_e32 v169, 16, v234
	v_mul_f32_e32 v22, v22, v169
	v_mul_f32_e32 v168, v87, v152
	v_fmac_f32_e32 v168, v23, v83
	v_add_f32_e32 v23, v166, v168
	v_and_b32_e32 v169, 0xffff0000, v234
	v_mul_f32_e32 v23, v23, v169
	v_mul_f32_e32 v168, v88, v152
	v_fmac_f32_e32 v168, v24, v84
	v_add_f32_e32 v24, v166, v168
	v_lshlrev_b32_e32 v169, 16, v235
	v_mul_f32_e32 v24, v24, v169
	v_mul_f32_e32 v168, v89, v152
	v_fmac_f32_e32 v168, v25, v85
	v_add_f32_e32 v25, v166, v168
	v_and_b32_e32 v169, 0xffff0000, v235
	v_mul_f32_e32 v25, v25, v169
	v_cvt_pk_bf16_f32 v22, v22, v23
	v_cvt_pk_bf16_f32 v23, v24, v25
	global_store_dwordx2 v[146:147], v[22:23], off offset:1552
	v_mul_f32_e32 v168, v78, v152
	v_fmac_f32_e32 v168, v26, v74
	v_add_f32_e32 v26, v166, v168
	v_lshlrev_b32_e32 v169, 16, v236
	v_mul_f32_e32 v26, v26, v169
	v_mul_f32_e32 v168, v79, v152
	v_fmac_f32_e32 v168, v27, v75
	v_add_f32_e32 v27, v166, v168
	v_and_b32_e32 v169, 0xffff0000, v236
	v_mul_f32_e32 v27, v27, v169
	v_mul_f32_e32 v168, v80, v152
	v_fmac_f32_e32 v168, v28, v76
	v_add_f32_e32 v28, v166, v168
	v_lshlrev_b32_e32 v169, 16, v237
	v_mul_f32_e32 v28, v28, v169
	v_mul_f32_e32 v168, v81, v152
	v_fmac_f32_e32 v168, v29, v77
	v_add_f32_e32 v29, v166, v168
	v_and_b32_e32 v169, 0xffff0000, v237
	v_mul_f32_e32 v29, v29, v169
	v_cvt_pk_bf16_f32 v26, v26, v27
	v_cvt_pk_bf16_f32 v27, v28, v29
	global_store_dwordx2 v[146:147], v[26:27], off offset:1568
	v_mul_f32_e32 v168, v70, v152
	v_fmac_f32_e32 v168, v30, v66
	v_add_f32_e32 v30, v166, v168
	v_lshlrev_b32_e32 v169, 16, v238
	v_mul_f32_e32 v30, v30, v169
	v_mul_f32_e32 v168, v71, v152
	v_fmac_f32_e32 v168, v31, v67
	v_add_f32_e32 v31, v166, v168
	v_and_b32_e32 v169, 0xffff0000, v238
	v_mul_f32_e32 v31, v31, v169
	v_mul_f32_e32 v168, v72, v152
	v_fmac_f32_e32 v168, v32, v68
	v_add_f32_e32 v32, v166, v168
	v_lshlrev_b32_e32 v169, 16, v239
	v_mul_f32_e32 v32, v32, v169
	v_mul_f32_e32 v168, v73, v152
	v_fmac_f32_e32 v168, v33, v69
	v_add_f32_e32 v33, v166, v168
	v_and_b32_e32 v169, 0xffff0000, v239
	v_mul_f32_e32 v33, v33, v169
	v_cvt_pk_bf16_f32 v30, v30, v31
	v_cvt_pk_bf16_f32 v31, v32, v33
	global_store_dwordx2 v[146:147], v[30:31], off offset:1584
	v_mul_f32_e32 v168, v94, v153
	v_fmac_f32_e32 v168, v2, v90
	v_add_f32_e32 v2, v167, v168
	v_lshlrev_b32_e32 v169, 16, v240
	v_mul_f32_e32 v2, v2, v169
	v_mul_f32_e32 v168, v95, v153
	v_fmac_f32_e32 v168, v3, v91
	v_add_f32_e32 v3, v167, v168
	v_and_b32_e32 v169, 0xffff0000, v240
	v_mul_f32_e32 v3, v3, v169
	v_mul_f32_e32 v168, v96, v153
	v_fmac_f32_e32 v168, v4, v92
	v_add_f32_e32 v4, v167, v168
	v_lshlrev_b32_e32 v169, 16, v241
	v_mul_f32_e32 v4, v4, v169
	v_mul_f32_e32 v168, v97, v153
	v_fmac_f32_e32 v168, v5, v93
	v_add_f32_e32 v5, v167, v168
	v_and_b32_e32 v169, 0xffff0000, v241
	v_mul_f32_e32 v5, v5, v169
	v_cvt_pk_bf16_f32 v2, v2, v3
	v_cvt_pk_bf16_f32 v3, v4, v5
	global_store_dwordx2 v[148:149], v[2:3], off offset:1536
	v_mul_f32_e32 v168, v86, v153
	v_fmac_f32_e32 v168, v6, v82
	v_add_f32_e32 v6, v167, v168
	v_lshlrev_b32_e32 v169, 16, v246
	v_mul_f32_e32 v6, v6, v169
	v_mul_f32_e32 v168, v87, v153
	v_fmac_f32_e32 v168, v7, v83
	v_add_f32_e32 v7, v167, v168
	v_and_b32_e32 v169, 0xffff0000, v246
	v_mul_f32_e32 v7, v7, v169
	v_mul_f32_e32 v168, v88, v153
	v_fmac_f32_e32 v168, v8, v84
	v_add_f32_e32 v8, v167, v168
	v_lshlrev_b32_e32 v169, 16, v247
	v_mul_f32_e32 v8, v8, v169
	v_mul_f32_e32 v168, v89, v153
	v_fmac_f32_e32 v168, v9, v85
	v_add_f32_e32 v9, v167, v168
	v_and_b32_e32 v169, 0xffff0000, v247
	v_mul_f32_e32 v9, v9, v169
	v_cvt_pk_bf16_f32 v6, v6, v7
	v_cvt_pk_bf16_f32 v7, v8, v9
	global_store_dwordx2 v[148:149], v[6:7], off offset:1552
	v_mul_f32_e32 v168, v78, v153
	v_fmac_f32_e32 v168, v10, v74
	v_add_f32_e32 v10, v167, v168
	v_lshlrev_b32_e32 v169, 16, v252
	v_mul_f32_e32 v10, v10, v169
	v_mul_f32_e32 v168, v79, v153
	v_fmac_f32_e32 v168, v11, v75
	v_add_f32_e32 v11, v167, v168
	v_and_b32_e32 v169, 0xffff0000, v252
	v_mul_f32_e32 v11, v11, v169
	v_mul_f32_e32 v168, v80, v153
	v_fmac_f32_e32 v168, v12, v76
	v_add_f32_e32 v12, v167, v168
	v_lshlrev_b32_e32 v169, 16, v253
	v_mul_f32_e32 v12, v12, v169
	v_mul_f32_e32 v168, v81, v153
	v_fmac_f32_e32 v168, v13, v77
	v_add_f32_e32 v13, v167, v168
	v_and_b32_e32 v169, 0xffff0000, v253
	v_mul_f32_e32 v13, v13, v169
	v_cvt_pk_bf16_f32 v10, v10, v11
	v_cvt_pk_bf16_f32 v11, v12, v13
	global_store_dwordx2 v[148:149], v[10:11], off offset:1568
	v_mul_f32_e32 v168, v70, v153
	v_fmac_f32_e32 v168, v14, v66
	v_add_f32_e32 v14, v167, v168
	v_lshlrev_b32_e32 v169, 16, v254
	v_mul_f32_e32 v14, v14, v169
	v_mul_f32_e32 v168, v71, v153
	v_fmac_f32_e32 v168, v15, v67
	v_add_f32_e32 v15, v167, v168
	v_and_b32_e32 v169, 0xffff0000, v254
	v_mul_f32_e32 v15, v15, v169
	v_mul_f32_e32 v168, v72, v153
	v_fmac_f32_e32 v168, v16, v68
	v_add_f32_e32 v16, v167, v168
	v_lshlrev_b32_e32 v169, 16, v255
	v_mul_f32_e32 v16, v16, v169
	v_mul_f32_e32 v168, v73, v153
	v_fmac_f32_e32 v168, v17, v69
	v_add_f32_e32 v17, v167, v168
	v_and_b32_e32 v169, 0xffff0000, v255
	v_mul_f32_e32 v17, v17, v169
	v_cvt_pk_bf16_f32 v14, v14, v15
	v_cvt_pk_bf16_f32 v15, v16, v17
	global_store_dwordx2 v[148:149], v[14:15], off offset:1584
	s_barrier
	s_cbranch_scc0 .LBB0_849
